# grid barrier: drop the dead per-XCD generation bump (nobody polls it since the TOPGEN poll) and its vmcnt wait on the XCD leader's release path
# baseline (speedup 1.0000x reference)
; #define PG8_LAS __attribute__((address_space(3)))
; #define PG8_BAR __builtin_amdgcn_s_barrier()
; template <class Epi, class Sched, bool ALIGN_EPI = false, bool SP2 = false>
; __device__ __forceinline__ void gemm_phase(PG8_LAS unsigned char* lds, const Gemm g, const Sched& S, const Epi& E, const int tid_arg) {
;     int tid_l = tid_arg; asm volatile("" : "+v"(tid_l));
;     const int tid = tid_l, wid = __builtin_amdgcn_readfirstlane(tid >> 6), lane = tid & 63, wr = wid >> 2, wc = wid & 3, fr = lane & 15, fq = lane >> 4;
;     const int K = g.K, nt = K / BK;
;     unsigned voffA[2], voffB[2];
; #pragma unroll
;     for (int i = 0; i < 2; ++i) { int R, C; stage_rc(tid * 16 + i * 8192, R, C); const int Rb = Epi::PERM ? ((R & ~31) + perm32(R & 31)) : R;
;         voffA[i] = (unsigned)(R * K + C) * 2u; voffB[i] = (unsigned)(Rb * K + C) * 2u; }
;     const size_t kstep = (size_t)(BK * 2);
;     const size_t hstep = (size_t)HALF * K * 2;
;     const size_t tstep = 2 * hstep;
;     const unsigned ldsw = (unsigned)wid * 1024u;
;     const int aoff = lds_byte(wr * 64 + fr, fq * 8), boff = lds_byte(wc * 32 + fr, fq * 8);
;     ...
;     Unit cur, nxt; int ui = 0;
;     if (!S.next(0, cur)) return;
;     f32x4 acc[2][2][4][2];
; #pragma unroll
;     for (int a = 0; a < 2; ++a)
; #pragma unroll
;         for (int b = 0; b < 2; ++b)
; #pragma unroll
;             for (int m = 0; m < 4; ++m)
; #pragma unroll
;                 for (int n = 0; n < 2; ++n) acc[a][b][m][n] = (f32x4){0.f, 0.f, 0.f, 0.f};
;     bf16x8 At[4][2], B0[2][2], B1[2][2];
;     const char* cA = (const char*)g.A + (size_t)cur.pm * tstep; const char* cB = (const char*)g.Bt + (size_t)cur.pn * tstep;
;     S.a_ready(cur);
;     if constexpr (SP2) {
;         PG8_STAGE(PG8_SB(0, 0), cB, voffB); PG8_STAGE(PG8_SB(0, 1), cB + hstep, voffB); PG8_STAGE(PG8_SA(0, 0), cA, voffA); PG8_STAGE(PG8_SA(0, 1), cA + hstep, voffA);
;         if (wr == 1) PG8_BAR;
;         PG8_WAIT_V(2); PG8_BAR;
;         PG8_STAGE(PG8_SB(1, 0), cB + kstep, voffB); PG8_STAGE(PG8_SA(1, 0), cA + kstep, voffA); PG8_STAGE(PG8_SB(1, 1), cB + hstep + kstep, voffB);
;         PG8_WAIT_V(6); PG8_BAR;
;     } else {
;         PG8_STAGE(PG8_SB(0, 0), cB, voffB); PG8_STAGE(PG8_SA(0, 0), cA, voffA); PG8_STAGE(PG8_SB(0, 1), cB + hstep, voffB); PG8_STAGE(PG8_SA(0, 1), cA + hstep, voffA);
;         if (wr == 1) PG8_BAR;
;         PG8_WAIT_V(4); PG8_BAR;
.LBB0_80:
	s_or_b64 exec, exec, s[8:9]
	s_mov_b64 s[8:9], exec
	v_mbcnt_lo_u32_b32 v2, s8, 0
	v_mbcnt_hi_u32_b32 v2, s9, v2
	v_cmp_eq_u32_e32 vcc, 0, v2
	s_waitcnt vmcnt(0)
	s_and_saveexec_b64 s[10:11], vcc
	s_cbranch_execz .LBB0_82
	s_bcnt1_i32_b64 s1, s[8:9]
	v_mov_b32_e32 v2, 0x2000
	v_mov_b32_e32 v3, s1
.LBB0_82:
	s_or_b64 exec, exec, s[10:11]
.LBB0_83:
	s_or_b64 exec, exec, s[4:5]
	s_load_dwordx4 s[8:11], s[90:91], 0xa8
	s_mov_b64 s[4:5], 0
	s_waitcnt lgkmcnt(0)
	s_barrier
	s_add_u32 s12, s10, s4
	s_addc_u32 s13, s11, s5
	s_cmpk_lt_i32 s60, 0xb2c
	s_cselect_b64 s[2:3], -1, 0
	v_mov_b32_e32 v11, v201
	s_ashr_i32 s75, s70, 31
	s_mov_b32 s74, s70
	s_ashr_i32 s61, s60, 31
	v_writelane_b32 v251, s2, 8
	v_readfirstlane_b32 s7, v11
	s_and_b64 vcc, exec, s[2:3]
	v_writelane_b32 v251, s3, 9
	s_cbranch_vccz .LBB0_103
	v_lshlrev_b32_e32 v2, 4, v11
	v_add_u32_e32 v3, 0x2000, v2
	v_ashrrev_i32_e32 v4, 31, v3
	v_lshrrev_b32_e32 v4, 22, v4
	v_add_u32_e32 v4, v3, v4
	v_ashrrev_i32_e32 v10, 10, v4
	v_mul_i32_i24_e32 v4, 0x400, v10
	v_sub_u32_e32 v3, v3, v4
	v_lshrrev_b32_e32 v4, 4, v3
	v_bitop3_b32 v3, v4, v3, 32 bitop3:0x6c
	v_ashrrev_i32_e32 v4, 31, v3
	v_lshrrev_b32_e32 v4, 26, v4
	v_add_u32_e32 v4, v3, v4
	v_lshlrev_b32_e32 v5, 3, v10
	v_ashrrev_i32_e32 v12, 6, v4
	v_and_b32_e32 v5, -16, v5
	v_add_u32_e32 v5, v12, v5
	v_and_b32_e32 v6, 3, v12
	s_mov_b32 s6, 0x1fffe0
	v_lshrrev_b32_e32 v7, 2, v5
	v_lshlrev_b32_e32 v8, 1, v5
	v_and_b32_e32 v4, 0xc0, v4
	v_and_or_b32 v6, v5, s6, v6
	v_and_b32_e32 v7, 4, v7
	v_and_b32_e32 v8, 24, v8
	v_sub_u32_e32 v3, v3, v4
	v_mov_b32_e32 v4, 1
	v_or3_b32 v6, v6, v7, v8
	v_lshlrev_b32_e32 v7, 5, v10
	v_ashrrev_i16_sdwa v3, v4, sext(v3) dst_sel:DWORD dst_unused:UNUSED_PAD src0_sel:DWORD src1_sel:BYTE_0
	v_and_b32_e32 v7, 32, v7
	v_bfe_i32 v13, v3, 0, 16
	v_add_lshl_u32 v3, v7, v13, 1
	v_lshl_add_u32 v130, v6, 11, v3
	v_lshl_add_u32 v132, v5, 11, v3
	v_bfe_i32 v3, v11, 27, 1
	v_lshrrev_b32_e32 v3, 22, v3
	v_add_u32_e32 v3, v2, v3
	v_and_b32_e32 v3, 0xfffffc00, v3
	v_sub_u32_e32 v2, v2, v3
	v_lshrrev_b32_e32 v3, 4, v2
	v_ashrrev_i32_e32 v5, 31, v11
	v_bitop3_b32 v2, v3, v2, 32 bitop3:0x6c
	v_lshrrev_b32_e32 v5, 26, v5
	v_ashrrev_i32_e32 v3, 31, v2
	v_add_u32_e32 v5, v11, v5
	v_lshrrev_b32_e32 v3, 26, v3
	v_ashrrev_i32_e32 v15, 6, v5
	v_add_u32_e32 v3, v2, v3
	v_lshlrev_b32_e32 v5, 3, v15
	v_ashrrev_i32_e32 v14, 6, v3
	v_and_b32_e32 v5, -16, v5
	s_add_u32 s1, s12, 0x4780000
	v_add_u32_e32 v5, v14, v5
	v_and_b32_e32 v6, 3, v14
	s_addc_u32 s2, s13, 0
	v_and_or_b32 v6, v5, s6, v6
	s_lshr_b32 s6, s61, 29
	s_add_i32 s6, s60, s6
	s_and_b32 s8, s6, -8
	s_sub_i32 s8, s60, s8
	s_ashr_i32 s14, s7, 6
	s_mul_i32 s10, s8, 0x165
	s_ashr_i32 s16, s7, 8
	s_lshl_b32 s3, s14, 10
	s_add_i32 s10, s10, 4
	s_ashr_i32 s6, s6, 3
	s_mul_i32 s9, s8, 0x166
	s_cmp_lt_i32 s8, 4
	s_cselect_b32 s8, s9, s10
	s_add_i32 s8, s8, s6
	s_mul_hi_i32 s6, s8, 0x2e8ba2e9
	s_lshr_b32 s9, s6, 31
	s_ashr_i32 s6, s6, 4
	v_lshrrev_b32_e32 v7, 2, v5
	v_lshlrev_b32_e32 v8, 1, v5
	v_and_b32_e32 v3, 0xc0, v3
	s_add_i32 s6, s6, s9
	v_and_b32_e32 v7, 4, v7
	v_and_b32_e32 v8, 24, v8
	v_sub_u32_e32 v2, v2, v3
	s_lshl_b32 s10, s6, 2
	v_or3_b32 v6, v6, v7, v8
	v_lshlrev_b32_e32 v7, 5, v15
	v_ashrrev_i16_sdwa v2, v4, sext(v2) dst_sel:DWORD dst_unused:UNUSED_PAD src0_sel:DWORD src1_sel:BYTE_0
	s_sub_i32 s9, 0x82, s10
	s_mulk_i32 s6, 0x58
	v_and_b32_e32 v7, 32, v7
	v_bfe_i32 v16, v2, 0, 16
	s_min_u32 s11, s9, 4
	s_sub_i32 s15, s8, s6
	v_add_lshl_u32 v2, v7, v16, 1
	s_sext_i32_i8 s6, s15
	v_cvt_f32_ubyte0_e32 v4, s11
	v_lshl_add_u32 v134, v6, 11, v2
	v_cvt_f32_i32_e32 v3, s6
	v_rcp_iflag_f32_e32 v6, v4
	v_lshl_add_u32 v136, v5, 11, v2
	s_ashr_i32 s6, s6, 30
	s_or_b32 s6, s6, 1
	v_mul_f32_e32 v2, v3, v6
	v_trunc_f32_e32 v2, v2
	v_fma_f32 v3, -v2, v4, v3
	v_cvt_i32_f32_e32 v2, v2
	v_cmp_ge_f32_e64 s[8:9], |v3|, v4
	s_and_b64 s[8:9], s[8:9], exec
	s_cselect_b32 s6, s6, 0
	v_readfirstlane_b32 s8, v2
	s_add_i32 s6, s8, s6
	s_mul_i32 s8, s6, s11
	s_sub_i32 s8, s15, s8
	s_sext_i32_i8 s8, s8
	s_add_i32 s26, s10, s8
	s_ashr_i32 s27, s26, 31
	s_bfe_i64 s[10:11], s[6:7], 0x80000
	s_lshl_b64 s[8:9], s[26:27], 19
	s_lshl_b64 s[10:11], s[10:11], 19
	s_add_u32 s30, s12, s10
	s_addc_u32 s31, s13, s11
	s_add_i32 s27, s3, 0
	s_add_i32 m0, s27, 0x10000
	v_mov_b32_e32 v135, 0
	global_load_lds_dwordx4 v134, s[30:31]
	s_add_i32 m0, s27, 0x12000
	s_add_u32 s10, s30, 0x40000
	global_load_lds_dwordx4 v130, s[30:31]
	s_addc_u32 s11, s31, 0
	s_add_i32 m0, s27, 0x14000
	v_mov_b32_e32 v131, v135
	global_load_lds_dwordx4 v134, s[10:11]
	s_add_i32 m0, s27, 0x16000
	s_add_u32 s28, s1, s8
	s_addc_u32 s29, s2, s9
	s_add_i32 s33, s27, 0x2000
	global_load_lds_dwordx4 v130, s[10:11]
	s_mov_b32 m0, s27
	s_add_u32 s8, s28, 0x40000
	global_load_lds_dwordx4 v136, s[28:29]
	s_mov_b32 m0, s33
	s_addc_u32 s9, s29, 0
	s_add_i32 s36, s27, 0x4000
	global_load_lds_dwordx4 v132, s[28:29]
	s_mov_b32 m0, s36
	s_add_i32 s37, s27, 0x6000
	global_load_lds_dwordx4 v136, s[8:9]
	s_mov_b32 m0, s37
	v_mov_b32_e32 v137, v135
	global_load_lds_dwordx4 v132, s[8:9]
	v_mov_b32_e32 v133, v135
	s_cmp_eq_u32 s16, 1
	s_mov_b32 s38, 0
	v_lshl_add_u64 v[8:9], s[30:31], 0, v[134:135]
	v_lshl_add_u64 v[6:7], s[30:31], 0, v[130:131]
	v_lshl_add_u64 v[2:3], s[28:29], 0, v[136:137]
	s_cselect_b64 s[8:9], -1, 0
	s_cmp_lg_u32 s16, 1
	v_lshl_add_u64 v[4:5], s[28:29], 0, v[132:133]
	s_cbranch_scc1 .LBB0_86
	s_barrier

; template <class Epi, class Sched, bool ALIGN_EPI = false, bool SP2 = false>
; __device__ __forceinline__ void gemm_phase(PG8_LAS unsigned char* lds, const Gemm g, const Sched& S, const Epi& E, const int tid_arg) {
;     ...
;         const bool has_next = S.next(ui + 1, nxt);
;         const char* nA = has_next ? (const char*)g.A + (size_t)nxt.pm * tstep : cA; const char* nB = has_next ? (const char*)g.Bt + (size_t)nxt.pn * tstep : cB;
;     ...
;         for (int a = 0; a < 2; ++a)
; #pragma unroll
;             for (int b = 0; b < 2; ++b)
; #pragma unroll
;                 for (int m = 0; m < 4; ++m)
; #pragma unroll
;                     for (int n = 0; n < 2; ++n) acc[a][b][m][n] = (f32x4){0.f, 0.f, 0.f, 0.f};
;         cur = nxt; cA = nA; cB = nB; ++ui;
.LBB0_95:
	s_ashr_i32 s21, s20, 31
	s_lshl_b64 s[22:23], s[20:21], 19
	s_add_u32 s22, s1, s22
	s_addc_u32 s23, s2, s23
	s_and_b64 s[24:25], s[6:7], exec
	s_cselect_b32 s21, s23, s29
	s_cselect_b32 s45, s22, s28
	s_ashr_i32 s19, s18, 31
	s_lshl_b64 s[24:25], s[18:19], 19
	s_add_u32 s24, s12, s24
	s_addc_u32 s25, s13, s25
	s_and_b64 s[34:35], s[6:7], exec
	s_cselect_b32 s19, s25, s31
	s_cselect_b32 s46, s24, s30
	s_add_u32 s28, s28, 0x40080
	s_addc_u32 s29, s29, 0
	s_add_u32 s47, s30, 0x100
	v_mov_b32_e32 v2, 0
	s_addc_u32 s48, s31, 0
	s_mov_b32 s49, -2
	v_mov_b32_e32 v3, v2
	v_mov_b32_e32 v4, v2
	v_mov_b32_e32 v5, v2
	v_mov_b32_e32 v6, v2
	v_mov_b32_e32 v7, v2
	v_mov_b32_e32 v8, v2
	v_mov_b32_e32 v9, v2
	v_mov_b32_e32 v18, v2
	v_mov_b32_e32 v19, v2
	v_mov_b32_e32 v20, v2
	v_mov_b32_e32 v21, v2
	v_mov_b32_e32 v22, v2
	v_mov_b32_e32 v23, v2
	v_mov_b32_e32 v24, v2
	v_mov_b32_e32 v25, v2
	v_mov_b32_e32 v34, v2
	v_mov_b32_e32 v35, v2
	v_mov_b32_e32 v36, v2
	v_mov_b32_e32 v37, v2
	v_mov_b32_e32 v38, v2
	v_mov_b32_e32 v39, v2
	v_mov_b32_e32 v40, v2
	v_mov_b32_e32 v41, v2
	v_mov_b32_e32 v50, v2
	v_mov_b32_e32 v51, v2
	v_mov_b32_e32 v52, v2
	v_mov_b32_e32 v53, v2
	v_mov_b32_e32 v54, v2
	v_mov_b32_e32 v55, v2
	v_mov_b32_e32 v56, v2
	v_mov_b32_e32 v57, v2
	v_mov_b32_e32 v10, v2
	v_mov_b32_e32 v11, v2
	v_mov_b32_e32 v12, v2
	v_mov_b32_e32 v13, v2
	v_mov_b32_e32 v14, v2
	v_mov_b32_e32 v15, v2
	v_mov_b32_e32 v16, v2
	v_mov_b32_e32 v17, v2
	v_mov_b32_e32 v26, v2
	v_mov_b32_e32 v27, v2
	v_mov_b32_e32 v28, v2
	v_mov_b32_e32 v29, v2
	v_mov_b32_e32 v30, v2
	v_mov_b32_e32 v31, v2
	v_mov_b32_e32 v32, v2
	v_mov_b32_e32 v33, v2
	v_mov_b32_e32 v42, v2
	v_mov_b32_e32 v43, v2
	v_mov_b32_e32 v44, v2
	v_mov_b32_e32 v45, v2
	v_mov_b32_e32 v46, v2
	v_mov_b32_e32 v47, v2
	v_mov_b32_e32 v48, v2
	v_mov_b32_e32 v49, v2
	v_mov_b32_e32 v58, v2
	v_mov_b32_e32 v59, v2
	v_mov_b32_e32 v60, v2
	v_mov_b32_e32 v61, v2
	v_mov_b32_e32 v62, v2
	v_mov_b32_e32 v63, v2
	v_mov_b32_e32 v64, v2
	v_mov_b32_e32 v65, v2
	v_mov_b32_e32 v66, v2
	v_mov_b32_e32 v67, v2
	v_mov_b32_e32 v68, v2
	v_mov_b32_e32 v69, v2
	v_mov_b32_e32 v70, v2
	v_mov_b32_e32 v71, v2
	v_mov_b32_e32 v72, v2
	v_mov_b32_e32 v73, v2
	v_mov_b32_e32 v82, v2
	v_mov_b32_e32 v83, v2
	v_mov_b32_e32 v84, v2
	v_mov_b32_e32 v85, v2
	v_mov_b32_e32 v86, v2
	v_mov_b32_e32 v87, v2
	v_mov_b32_e32 v88, v2
	v_mov_b32_e32 v89, v2
	v_mov_b32_e32 v98, v2
	v_mov_b32_e32 v99, v2
	v_mov_b32_e32 v100, v2
	v_mov_b32_e32 v101, v2
	v_mov_b32_e32 v102, v2
	v_mov_b32_e32 v103, v2
	v_mov_b32_e32 v104, v2
	v_mov_b32_e32 v105, v2
	v_mov_b32_e32 v114, v2
	v_mov_b32_e32 v115, v2
	v_mov_b32_e32 v116, v2
	v_mov_b32_e32 v117, v2
	v_mov_b32_e32 v118, v2
	v_mov_b32_e32 v119, v2
	v_mov_b32_e32 v120, v2
	v_mov_b32_e32 v121, v2
	v_mov_b32_e32 v74, v2
	v_mov_b32_e32 v75, v2
	v_mov_b32_e32 v76, v2
	v_mov_b32_e32 v77, v2
	v_mov_b32_e32 v78, v2
	v_mov_b32_e32 v79, v2
	v_mov_b32_e32 v80, v2
	v_mov_b32_e32 v81, v2
	v_mov_b32_e32 v90, v2
	v_mov_b32_e32 v91, v2
	v_mov_b32_e32 v92, v2
	v_mov_b32_e32 v93, v2
	v_mov_b32_e32 v94, v2
	v_mov_b32_e32 v95, v2
	v_mov_b32_e32 v96, v2
	v_mov_b32_e32 v97, v2
	v_mov_b32_e32 v106, v2
	v_mov_b32_e32 v107, v2
	v_mov_b32_e32 v108, v2
	v_mov_b32_e32 v109, v2
	v_mov_b32_e32 v110, v2
	v_mov_b32_e32 v111, v2
	v_mov_b32_e32 v112, v2
	v_mov_b32_e32 v113, v2
	v_mov_b32_e32 v122, v2
	v_mov_b32_e32 v123, v2
	v_mov_b32_e32 v124, v2
	v_mov_b32_e32 v125, v2
	v_mov_b32_e32 v126, v2
	v_mov_b32_e32 v127, v2
	v_mov_b32_e32 v128, v2
	v_mov_b32_e32 v129, v2
	s_nop 0
	s_nop 0
	s_nop 0
	s_nop 0
	s_nop 0
	s_nop 0
	s_nop 0
	s_nop 0
	s_nop 0
	s_nop 0
	s_nop 0
	s_nop 0

; __device__ __forceinline__ unsigned xb_ld(unsigned* p)              { return __hip_atomic_load(p, __ATOMIC_RELAXED, __HIP_MEMORY_SCOPE_AGENT); }
; __device__ __forceinline__ unsigned xb_add(unsigned* p, unsigned v) { return __hip_atomic_fetch_add(p, v, __ATOMIC_RELAXED, __HIP_MEMORY_SCOPE_AGENT); }
; #define XB_SPIN(cond, bar) do { unsigned _sp = 0; while (cond) { __builtin_amdgcn_s_sleep(1); \
;     if ((++_sp & 255u) == 0u) { if (xb_ld(&(bar)[XB_TMO])) break; if (_sp > XB_SPIN_CAP) { atomicAdd(&(bar)[XB_TMO], 1u); break; } } } } while (0)
;     __host__ __device__ bool next(int i, Unit& u) const {
;         const long L = (long)i * G + c; if (L >= nwg) return false;
;         int wgid = (int)L; { const int q = nwg / NXCD, r = nwg % NXCD, xcd = wgid % NXCD, off = wgid / NXCD; wgid = (xcd < r ? xcd * (q + 1) : r * (q + 1) + (xcd - r) * q) + off; }
;         const int nig = WGM * nN, gid = wgid / nig, fm = gid * WGM, gsz = (nM - fm) < WGM ? (nM - fm) : WGM;
;         u.pm = fm + ((wgid % nig) % gsz); u.pn = (wgid % nig) / gsz; return true;
; __device__ __forceinline__ void xcd_barrier(const XcdBarrier& b, const bool leader) {
;     ...
;             xb_add(&bar[XB_XGEN(b.x)], 1u);
;             asm volatile("s_waitcnt vmcnt(0)" ::: "memory");
;         } else {
;             XB_SPIN(xb_ld(&bar[XB_XGEN(b.x)]) == gen, bar);
;             __builtin_amdgcn_fence(__ATOMIC_ACQUIRE, "agent");
;             asm volatile("s_waitcnt vmcnt(0)" ::: "memory");
;         }
;     }
;     __syncthreads();
.LBB0_238:
	s_or_b64 exec, exec, s[8:9]
	s_mov_b64 s[8:9], exec
	v_mbcnt_lo_u32_b32 v2, s8, 0
	v_mbcnt_hi_u32_b32 v2, s9, v2
	v_cmp_eq_u32_e32 vcc, 0, v2
	s_waitcnt vmcnt(0)
	s_and_saveexec_b64 s[10:11], vcc
	s_cbranch_execz .LBB0_240
	s_bcnt1_i32_b64 s1, s[8:9]
	v_mov_b32_e32 v2, 0x2000
	v_mov_b32_e32 v3, s1
.LBB0_240:
	s_or_b64 exec, exec, s[10:11]
.LBB0_241:
	s_or_b64 exec, exec, s[4:5]
	s_cmpk_lt_i32 s60, 0x200
	s_mov_b64 s[4:5], 0
	s_cselect_b64 s[10:11], -1, 0
	s_mov_b64 s[6:7], s[90:91]
	s_mov_b64 s[8:9], s[90:91]
	v_mov_b32_e32 v10, v201
	s_waitcnt lgkmcnt(0)
	s_barrier
	s_and_b64 vcc, exec, s[10:11]
	v_readfirstlane_b32 s12, v10
	s_cbranch_vccz .LBB0_243
	s_lshr_b32 s1, s61, 29
	s_add_i32 s1, s60, s1
	s_ashr_i32 s2, s1, 3
	s_and_b32 s1, s1, -8
	s_sub_i32 s1, s60, s1
	s_lshl_b32 s13, s1, 6
	s_mul_i32 s3, s1, 0x41
	s_cmp_lt_i32 s1, 0
	s_cselect_b32 s1, s3, s13
	s_add_i32 s1, s1, s2
	s_ashr_i32 s2, s1, 31
	s_lshr_b32 s2, s2, 28
	s_add_i32 s2, s1, s2
	s_ashr_i32 s3, s2, 4
	s_and_b32 s2, s2, 0xfff0
	s_sub_i32 s1, s1, s2
	s_bfe_i32 s2, s1, 0x80000
	s_bfe_u32 s2, s2, 0x2000d
	s_add_i32 s2, s1, s2
	s_bfe_i32 s13, s2, 0x80000
	s_and_b32 s2, s2, 0xfc
	s_sub_i32 s1, s1, s2
	s_lshl_b32 s3, s3, 2
	s_sext_i32_i16 s13, s13
	s_sext_i32_i8 s1, s1
	s_add_i32 s30, s3, s1
	s_ashr_i32 s55, s13, 2

; template <class Epi, class Sched, bool ALIGN_EPI = false, bool SP2 = false>
; __device__ __forceinline__ void gemm_phase(PG8_LAS unsigned char* lds, const Gemm g, const Sched& S, const Epi& E, const int tid_arg) {
;     ...
;         for (int a = 0; a < 2; ++a)
; #pragma unroll
;             for (int b = 0; b < 2; ++b)
; #pragma unroll
;                 for (int m = 0; m < 4; ++m)
; #pragma unroll
;                     for (int n = 0; n < 2; ++n) acc[a][b][m][n] = (f32x4){0.f, 0.f, 0.f, 0.f};
;         cur = nxt; cA = nA; cB = nB; ++ui;
.LBB0_259:
	s_add_u32 s16, s36, 0x100
	v_mov_b32_e32 v2, 0
	s_addc_u32 s31, s37, 0
	s_mov_b32 s56, -2
	s_waitcnt lgkmcnt(0)
	v_mov_b32_e32 v3, v2
	v_mov_b32_e32 v4, v2
	v_mov_b32_e32 v5, v2
	v_mov_b32_e32 v6, v2
	v_mov_b32_e32 v7, v2
	v_mov_b32_e32 v8, v2
	v_mov_b32_e32 v9, v2
	v_mov_b32_e32 v18, v2
	v_mov_b32_e32 v19, v2
	v_mov_b32_e32 v20, v2
	v_mov_b32_e32 v21, v2
	v_mov_b32_e32 v22, v2
	v_mov_b32_e32 v23, v2
	v_mov_b32_e32 v24, v2
	v_mov_b32_e32 v25, v2
	v_mov_b32_e32 v34, v2
	v_mov_b32_e32 v35, v2
	v_mov_b32_e32 v36, v2
	v_mov_b32_e32 v37, v2
	v_mov_b32_e32 v38, v2
	v_mov_b32_e32 v39, v2
	v_mov_b32_e32 v40, v2
	v_mov_b32_e32 v41, v2
	v_mov_b32_e32 v50, v2
	v_mov_b32_e32 v51, v2
	v_mov_b32_e32 v52, v2
	v_mov_b32_e32 v53, v2
	v_mov_b32_e32 v54, v2
	v_mov_b32_e32 v55, v2
	v_mov_b32_e32 v56, v2
	v_mov_b32_e32 v57, v2
	v_mov_b32_e32 v10, v2
	v_mov_b32_e32 v11, v2
	v_mov_b32_e32 v12, v2
	v_mov_b32_e32 v13, v2
	v_mov_b32_e32 v14, v2
	v_mov_b32_e32 v15, v2
	v_mov_b32_e32 v16, v2
	v_mov_b32_e32 v17, v2
	v_mov_b32_e32 v26, v2
	v_mov_b32_e32 v27, v2
	v_mov_b32_e32 v28, v2
	v_mov_b32_e32 v29, v2
	v_mov_b32_e32 v30, v2
	v_mov_b32_e32 v31, v2
	v_mov_b32_e32 v32, v2
	v_mov_b32_e32 v33, v2
	v_mov_b32_e32 v42, v2
	v_mov_b32_e32 v43, v2
	v_mov_b32_e32 v44, v2
	v_mov_b32_e32 v45, v2
	v_mov_b32_e32 v46, v2
	v_mov_b32_e32 v47, v2
	v_mov_b32_e32 v48, v2
	v_mov_b32_e32 v49, v2
	v_mov_b32_e32 v58, v2
	v_mov_b32_e32 v59, v2
	v_mov_b32_e32 v60, v2
	v_mov_b32_e32 v61, v2
	v_mov_b32_e32 v62, v2
	v_mov_b32_e32 v63, v2
	v_mov_b32_e32 v64, v2
	v_mov_b32_e32 v65, v2
	v_mov_b32_e32 v66, v2
	v_mov_b32_e32 v67, v2
	v_mov_b32_e32 v68, v2
	v_mov_b32_e32 v69, v2
	v_mov_b32_e32 v70, v2
	v_mov_b32_e32 v71, v2
	v_mov_b32_e32 v72, v2
	v_mov_b32_e32 v73, v2
	v_mov_b32_e32 v82, v2
	v_mov_b32_e32 v83, v2
	v_mov_b32_e32 v84, v2
	v_mov_b32_e32 v85, v2
	v_mov_b32_e32 v86, v2
	v_mov_b32_e32 v87, v2
	v_mov_b32_e32 v88, v2
	v_mov_b32_e32 v89, v2
	v_mov_b32_e32 v98, v2
	v_mov_b32_e32 v99, v2
	v_mov_b32_e32 v100, v2
	v_mov_b32_e32 v101, v2
	v_mov_b32_e32 v102, v2
	v_mov_b32_e32 v103, v2
	v_mov_b32_e32 v104, v2
	v_mov_b32_e32 v105, v2
	v_mov_b32_e32 v114, v2
	v_mov_b32_e32 v115, v2
	v_mov_b32_e32 v116, v2
	v_mov_b32_e32 v117, v2
	v_mov_b32_e32 v118, v2
	v_mov_b32_e32 v119, v2
	v_mov_b32_e32 v120, v2
	v_mov_b32_e32 v121, v2
	v_mov_b32_e32 v74, v2
	v_mov_b32_e32 v75, v2
	v_mov_b32_e32 v76, v2
	v_mov_b32_e32 v77, v2
	v_mov_b32_e32 v78, v2
	v_mov_b32_e32 v79, v2
	v_mov_b32_e32 v80, v2
	v_mov_b32_e32 v81, v2
	v_mov_b32_e32 v90, v2
	v_mov_b32_e32 v91, v2
	v_mov_b32_e32 v92, v2
	v_mov_b32_e32 v93, v2
	v_mov_b32_e32 v94, v2
	v_mov_b32_e32 v95, v2
	v_mov_b32_e32 v96, v2
	v_mov_b32_e32 v97, v2
	v_mov_b32_e32 v106, v2
	v_mov_b32_e32 v107, v2
	v_mov_b32_e32 v108, v2
	v_mov_b32_e32 v109, v2
	v_mov_b32_e32 v110, v2
	v_mov_b32_e32 v111, v2
	v_mov_b32_e32 v112, v2
	v_mov_b32_e32 v113, v2
	v_mov_b32_e32 v122, v2
	v_mov_b32_e32 v123, v2
	v_mov_b32_e32 v124, v2
	v_mov_b32_e32 v125, v2
	v_mov_b32_e32 v126, v2
	v_mov_b32_e32 v127, v2
	v_mov_b32_e32 v128, v2
	v_mov_b32_e32 v129, v2
	s_nop 0
	s_nop 0
	s_nop 0
	s_nop 0
	s_nop 0
	s_nop 0

; __device__ __forceinline__ unsigned xb_ld(unsigned* p)              { return __hip_atomic_load(p, __ATOMIC_RELAXED, __HIP_MEMORY_SCOPE_AGENT); }
; __device__ __forceinline__ unsigned xb_add(unsigned* p, unsigned v) { return __hip_atomic_fetch_add(p, v, __ATOMIC_RELAXED, __HIP_MEMORY_SCOPE_AGENT); }
; #define XB_SPIN(cond, bar) do { unsigned _sp = 0; while (cond) { __builtin_amdgcn_s_sleep(1); \
;     if ((++_sp & 255u) == 0u) { if (xb_ld(&(bar)[XB_TMO])) break; if (_sp > XB_SPIN_CAP) { atomicAdd(&(bar)[XB_TMO], 1u); break; } } } } while (0)
; #define MK_TID() (wave0 * 64 + (int)__builtin_amdgcn_mbcnt_hi(~0u, __builtin_amdgcn_mbcnt_lo(~0u, 0u)))
; __device__ __forceinline__ void xcd_barrier(const XcdBarrier& b, const bool leader) {
;     ...
;             xb_add(&bar[XB_XGEN(b.x)], 1u);
;             asm volatile("s_waitcnt vmcnt(0)" ::: "memory");
;         } else {
;             XB_SPIN(xb_ld(&bar[XB_XGEN(b.x)]) == gen, bar);
;             __builtin_amdgcn_fence(__ATOMIC_ACQUIRE, "agent");
;             asm volatile("s_waitcnt vmcnt(0)" ::: "memory");
;         }
;     }
;     __syncthreads();
; __global__ void __launch_bounds__(NTHREADS, 2) fwd_megakernel(Args a) {
;     ...
;     for (int grp = 0; grp < 2; ++grp) {
;         const int row0 = grp ? 16384 : 0, Mg = grp ? 16896 : 16384;
;     ...
;         for (int rp3 = 0; rp3 < REP_P3; ++rp3)
;         { pg8::Gemm g{XN + (size_t)row0 * 1024, WINT, Mg, NPROJ, 1024}; pg8::StaticOrder S; S.init(Mg, NPROJ, G, bx);
;           pg8::EpiProj E{PB, PBE, GG, FA, SS1 + (size_t)row0 * 16, out + O_KP, out + O_VP, out + O_KS, out + O_VS, row0};
;           pg8::gemm_phase<pg8::EpiProj, pg8::StaticOrder, true, true>(lds, g, S, E, MK_TID()); }
.LBB0_341:
	s_or_b64 exec, exec, s[4:5]
	s_mov_b64 s[4:5], exec
	v_mbcnt_lo_u32_b32 v2, s4, 0
	v_mbcnt_hi_u32_b32 v2, s5, v2
	v_cmp_eq_u32_e32 vcc, 0, v2
	s_waitcnt vmcnt(0)
	s_and_saveexec_b64 s[10:11], vcc
	s_cbranch_execz .LBB0_343
	s_bcnt1_i32_b64 s1, s[4:5]
	v_mov_b32_e32 v2, 0x2000
	v_mov_b32_e32 v3, s1
.LBB0_343:
	s_or_b64 exec, exec, s[10:11]
.LBB0_344:
	s_or_b64 exec, exec, s[6:7]
	s_load_dwordx4 s[8:11], s[90:91], 0xa8
	s_mov_b64 s[2:3], 0
	s_waitcnt lgkmcnt(0)
	s_barrier
	s_add_u32 s18, s10, s2
	s_addc_u32 s19, s11, s3
	s_lshl_b64 s[4:5], s[2:3], 2
	s_add_u32 s3, s8, s4
	s_addc_u32 s46, s9, s5
	s_lshr_b32 s1, s61, 29
	s_add_i32 s1, s60, s1
	s_and_b32 s2, s1, -8
	s_sub_i32 s4, s60, s2
	s_ashr_i32 s2, s1, 3
	s_mul_i32 s1, s71, s70
	s_mul_i32 s67, s1, s0
	s_not_b32 s0, s60
	s_add_i32 s6, s70, s0
	s_lshl_b32 s0, s60, 9
	v_writelane_b32 v251, s0, 10
	s_lshl_b32 s0, s70, 9
	s_cmp_gt_i32 s4, -1
	v_writelane_b32 v251, s0, 11
	s_cselect_b64 s[0:1], -1, 0
	v_writelane_b32 v251, s0, 12
	s_movk_i32 s96, 0x2000
	v_mov_b32_e32 v3, 0
	v_writelane_b32 v251, s1, 13
	s_lshl_b32 s0, s4, 5
	s_cmp_lt_i32 s4, 0
	s_mul_i32 s1, s4, 33
	s_cselect_b32 s0, s1, s0
	s_add_i32 s0, s0, s2
	s_ashr_i32 s1, s0, 31
	s_lshr_b32 s1, s1, 28
	v_writelane_b32 v251, s4, 14
	s_add_i32 s1, s0, s1
	v_writelane_b32 v251, s2, 15
	s_ashr_i32 s2, s1, 4
	s_and_b32 s1, s1, -16
	s_sub_i32 s1, s0, s1
	s_bfe_i32 s0, s1, 0x80000
	s_bfe_u32 s0, s0, 0x2000d
	s_add_i32 s4, s1, s0
	s_bfe_i32 s0, s4, 0x80000
	s_and_b32 s4, s4, 0xfc
	s_sub_i32 s1, s1, s4
	s_lshl_b32 s2, s2, 2
	s_sext_i32_i16 s5, s0
	s_sext_i32_i8 s1, s1
	s_add_i32 s4, s2, s1
	s_ashr_i32 s1, s5, 2
	v_writelane_b32 v251, s1, 16
	s_mov_b32 s2, s4
	s_lshr_b32 s0, s5, 2
	s_ashr_i32 s5, s4, 31
	v_writelane_b32 v251, s2, 17
	s_lshl_b64 s[4:5], s[4:5], 19
	s_bfe_i64 s[0:1], s[0:1], 0x100000
	v_writelane_b32 v251, s3, 18
	v_writelane_b32 v251, s4, 19
	s_lshl_b64 s[0:1], s[0:1], 19
	s_cmp_lg_u64 s[10:11], 0
	v_writelane_b32 v251, s5, 20
	v_writelane_b32 v251, s0, 21
	s_mov_b64 s[4:5], 0
	s_movk_i32 s33, 0x100
	v_writelane_b32 v251, s1, 22
	s_cselect_b64 s[0:1], -1, 0
	v_writelane_b32 v251, s0, 23
	v_mov_b32_e32 v140, 0x358637bd
	s_mov_b32 s92, 0x800000
	v_writelane_b32 v251, s1, 24
	v_writelane_b32 v251, s59, 25
	s_add_i32 s0, s59, 0xffffe000
	v_writelane_b32 v251, s0, 26
	s_add_u32 s0, s10, 0x131b0080
	v_writelane_b32 v251, s0, 27
	s_addc_u32 s0, s11, 0
	v_writelane_b32 v251, s0, 28
	s_lshl_b32 s0, s60, 11
	v_writelane_b32 v251, s0, 29
	s_lshl_b32 s0, s70, 11
	s_ashr_i32 s7, s6, 31
	v_writelane_b32 v251, s0, 30
	s_lshl_b64 s[0:1], s[6:7], 16
	s_add_u32 s0, s8, s0
	s_addc_u32 s1, s9, s1
	v_writelane_b32 v251, s0, 31
	s_lshl_b64 s[94:95], s[74:75], 16
	v_mov_b32_e32 v141, 0x1000
	v_writelane_b32 v251, s1, 32
	s_mov_b32 s0, s6
	v_writelane_b32 v251, s0, 33
	v_mov_b32_e32 v202, 0x2000
	v_mov_b32_e32 v203, 0x1d79b000
	v_writelane_b32 v251, s1, 34
	s_lshl_b64 s[0:1], s[6:7], 9
	s_add_u32 s0, s8, s0
	s_addc_u32 s1, s9, s1
	v_writelane_b32 v251, s0, 35
	v_mov_b32_e32 v204, 1
	v_mov_b32_e32 v205, 0xfffffeff
	v_writelane_b32 v251, s1, 36
	s_lshl_b64 s[0:1], s[74:75], 9
	v_writelane_b32 v251, s0, 37
	v_mov_b32_e32 v206, 0x410
	v_mov_b32_e32 v207, 0x2400
	v_writelane_b32 v251, s1, 38
	s_lshl_b32 s0, s60, 12
	v_writelane_b32 v251, s0, 39
	s_lshl_b32 s0, s70, 12
	v_writelane_b32 v251, s0, 40
	s_lshl_b64 s[0:1], s[60:61], 16
	s_add_u32 s0, s8, s0
	s_addc_u32 s1, s9, s1
	s_add_u32 s0, s0, 0x1000
	v_writelane_b32 v251, s0, 41
	s_addc_u32 s0, s1, 0
	v_writelane_b32 v251, s0, 42
	s_lshl_b32 s0, s60, 6
	v_writelane_b32 v251, s0, 43
	s_lshl_b32 s0, s70, 6
	v_writelane_b32 v251, s0, 44
	v_writelane_b32 v251, s60, 45
	s_lshl_b32 s0, s60, 1
	v_mov_b32_e32 v208, 0x41b17218
	v_writelane_b32 v251, s61, 46
	v_writelane_b32 v251, s0, 47
	s_lshl_b32 s0, s70, 1
	v_writelane_b32 v251, s0, 48
	s_add_u32 s0, s8, 0x6800040
	v_writelane_b32 v251, s0, 49
	s_addc_u32 s0, s9, 0
	v_writelane_b32 v251, s0, 50
	s_add_i32 s0, 0, 0x22000
	v_writelane_b32 v251, s0, 51
	s_add_i32 s0, 0, 0x22004
	v_writelane_b32 v251, s0, 52
	s_add_i32 s0, 0, 0x19c00
	v_writelane_b32 v251, s0, 53
	s_add_i32 s0, 0, 0x11800
	v_writelane_b32 v251, s0, 54
	s_add_i32 s0, 0, 0x1ac00
	v_writelane_b32 v251, s0, 55
	s_add_i32 s0, 0, 0x1bc00
	v_writelane_b32 v251, s0, 56
	s_add_i32 s0, 0, 0x1b400
	v_writelane_b32 v251, s0, 57
	s_mov_b32 s0, 0
	v_writelane_b32 v251, s0, 58
	v_writelane_b32 v251, s4, 59
	v_mov_b64_e32 v[142:143], 0x100
	v_mov_b64_e32 v[144:145], 0xff
	s_mov_b32 s93, 0xbfb8aa3b
	s_mov_b32 s1, 0x3f317217
	s_mov_b32 s72, 0x7f800000
	s_mov_b32 s73, 0x4200000
	v_writelane_b32 v251, s5, 60
	s_mov_b32 s79, 0
	s_mov_b64 s[4:5], -1
	s_mov_b64 s[76:77], 0x80
	s_mov_b64 s[80:81], 0x20000
	s_mov_b64 s[86:87], 0x2000
	s_mov_b64 s[84:85], 0x100000
	s_branch .LBB0_348

; template <class Epi, class Sched, bool ALIGN_EPI = false, bool SP2 = false>
; __device__ __forceinline__ void gemm_phase(PG8_LAS unsigned char* lds, const Gemm g, const Sched& S, const Epi& E, const int tid_arg) {
;     ...
;         const bool has_next = S.next(ui + 1, nxt);
;         const char* nA = has_next ? (const char*)g.A + (size_t)nxt.pm * tstep : cA; const char* nB = has_next ? (const char*)g.Bt + (size_t)nxt.pn * tstep : cB;
;     ...
;         for (int a = 0; a < 2; ++a)
; #pragma unroll
;             for (int b = 0; b < 2; ++b)
; #pragma unroll
;                 for (int m = 0; m < 4; ++m)
; #pragma unroll
;                     for (int n = 0; n < 2; ++n) acc[a][b][m][n] = (f32x4){0.f, 0.f, 0.f, 0.f};
;         cur = nxt; cA = nA; cB = nB; ++ui;
.LBB0_362:
	s_ashr_i32 s29, s28, 31
	s_lshl_b64 s[6:7], s[28:29], 19
	s_add_u32 s30, s50, s6
	s_addc_u32 s31, s51, s7
	s_and_b64 s[6:7], s[8:9], exec
	s_cselect_b32 s6, s31, s15
	s_cselect_b32 s7, s30, s14
	s_ashr_i32 s27, s26, 31
	s_lshl_b64 s[34:35], s[26:27], 19
	s_add_u32 s34, s52, s34
	s_addc_u32 s35, s53, s35
	s_and_b64 s[38:39], s[8:9], exec
	s_cselect_b32 s11, s35, s37
	s_cselect_b32 s13, s34, s36
	s_add_u32 s14, s14, 0x40080
	s_addc_u32 s15, s15, 0
	s_add_u32 s27, s36, 0x100
	v_mov_b32_e32 v4, 0
	s_addc_u32 s29, s37, 0
	s_mov_b32 s40, -2
	v_mov_b32_e32 v5, v4
	v_mov_b32_e32 v6, v4
	v_mov_b32_e32 v7, v4
	v_mov_b32_e32 v8, v4
	v_mov_b32_e32 v9, v4
	v_mov_b32_e32 v10, v4
	v_mov_b32_e32 v11, v4
	v_mov_b32_e32 v20, v4
	v_mov_b32_e32 v21, v4
	v_mov_b32_e32 v22, v4
	v_mov_b32_e32 v23, v4
	v_mov_b32_e32 v24, v4
	v_mov_b32_e32 v25, v4
	v_mov_b32_e32 v26, v4
	v_mov_b32_e32 v27, v4
	v_mov_b32_e32 v36, v4
	v_mov_b32_e32 v37, v4
	v_mov_b32_e32 v38, v4
	v_mov_b32_e32 v39, v4
	v_mov_b32_e32 v40, v4
	v_mov_b32_e32 v41, v4
	v_mov_b32_e32 v42, v4
	v_mov_b32_e32 v43, v4
	v_mov_b32_e32 v52, v4
	v_mov_b32_e32 v53, v4
	v_mov_b32_e32 v54, v4
	v_mov_b32_e32 v55, v4
	v_mov_b32_e32 v56, v4
	v_mov_b32_e32 v57, v4
	v_mov_b32_e32 v58, v4
	v_mov_b32_e32 v59, v4
	v_mov_b32_e32 v12, v4
	v_mov_b32_e32 v13, v4
	v_mov_b32_e32 v14, v4
	v_mov_b32_e32 v15, v4
	v_mov_b32_e32 v16, v4
	v_mov_b32_e32 v17, v4
	v_mov_b32_e32 v18, v4
	v_mov_b32_e32 v19, v4
	v_mov_b32_e32 v28, v4
	v_mov_b32_e32 v29, v4
	v_mov_b32_e32 v30, v4
	v_mov_b32_e32 v31, v4
	v_mov_b32_e32 v32, v4
	v_mov_b32_e32 v33, v4
	v_mov_b32_e32 v34, v4
	v_mov_b32_e32 v35, v4
	v_mov_b32_e32 v44, v4
	v_mov_b32_e32 v45, v4
	v_mov_b32_e32 v46, v4
	v_mov_b32_e32 v47, v4
	v_mov_b32_e32 v48, v4
	v_mov_b32_e32 v49, v4
	v_mov_b32_e32 v50, v4
	v_mov_b32_e32 v51, v4
	v_mov_b32_e32 v60, v4
	v_mov_b32_e32 v61, v4
	v_mov_b32_e32 v62, v4
	v_mov_b32_e32 v63, v4
	v_mov_b32_e32 v64, v4
	v_mov_b32_e32 v65, v4
	v_mov_b32_e32 v66, v4
	v_mov_b32_e32 v67, v4
	v_mov_b32_e32 v68, v4
	v_mov_b32_e32 v69, v4
	v_mov_b32_e32 v70, v4
	v_mov_b32_e32 v71, v4
	v_mov_b32_e32 v72, v4
	v_mov_b32_e32 v73, v4
	v_mov_b32_e32 v74, v4
	v_mov_b32_e32 v75, v4
	v_mov_b32_e32 v84, v4
	v_mov_b32_e32 v85, v4
	v_mov_b32_e32 v86, v4
	v_mov_b32_e32 v87, v4
	v_mov_b32_e32 v88, v4
	v_mov_b32_e32 v89, v4
	v_mov_b32_e32 v90, v4
	v_mov_b32_e32 v91, v4
	v_mov_b32_e32 v100, v4
	v_mov_b32_e32 v101, v4
	v_mov_b32_e32 v102, v4
	v_mov_b32_e32 v103, v4
	v_mov_b32_e32 v104, v4
	v_mov_b32_e32 v105, v4
	v_mov_b32_e32 v106, v4
	v_mov_b32_e32 v107, v4
	v_mov_b32_e32 v116, v4
	v_mov_b32_e32 v117, v4
	v_mov_b32_e32 v118, v4
	v_mov_b32_e32 v119, v4
	s_waitcnt vmcnt(0)
	v_mov_b32_e32 v120, v4
	v_mov_b32_e32 v121, v4
	v_mov_b32_e32 v122, v4
	v_mov_b32_e32 v123, v4
	v_mov_b32_e32 v76, v4
	v_mov_b32_e32 v77, v4
	v_mov_b32_e32 v78, v4
	v_mov_b32_e32 v79, v4
	v_mov_b32_e32 v80, v4
	v_mov_b32_e32 v81, v4
	v_mov_b32_e32 v82, v4
	v_mov_b32_e32 v83, v4
	v_mov_b32_e32 v92, v4
	v_mov_b32_e32 v93, v4
	v_mov_b32_e32 v94, v4
	v_mov_b32_e32 v95, v4
	v_mov_b32_e32 v96, v4
	v_mov_b32_e32 v97, v4
	v_mov_b32_e32 v98, v4
	v_mov_b32_e32 v99, v4
	v_mov_b32_e32 v108, v4
	v_mov_b32_e32 v109, v4
	v_mov_b32_e32 v110, v4
	v_mov_b32_e32 v111, v4
	v_mov_b32_e32 v112, v4
	v_mov_b32_e32 v113, v4
	v_mov_b32_e32 v114, v4
	v_mov_b32_e32 v115, v4
	v_mov_b32_e32 v124, v4
	v_mov_b32_e32 v125, v4
	v_mov_b32_e32 v126, v4
	v_mov_b32_e32 v127, v4
	v_mov_b32_e32 v128, v4
	v_mov_b32_e32 v129, v4
	v_mov_b32_e32 v130, v4
	v_mov_b32_e32 v131, v4
	s_nop 0
	s_nop 0
	s_nop 0
	s_nop 0

; __device__ __forceinline__ unsigned xb_ld(unsigned* p)              { return __hip_atomic_load(p, __ATOMIC_RELAXED, __HIP_MEMORY_SCOPE_AGENT); }
; __device__ __forceinline__ unsigned xb_add(unsigned* p, unsigned v) { return __hip_atomic_fetch_add(p, v, __ATOMIC_RELAXED, __HIP_MEMORY_SCOPE_AGENT); }
; #define XB_SPIN(cond, bar) do { unsigned _sp = 0; while (cond) { __builtin_amdgcn_s_sleep(1); \
;     if ((++_sp & 255u) == 0u) { if (xb_ld(&(bar)[XB_TMO])) break; if (_sp > XB_SPIN_CAP) { atomicAdd(&(bar)[XB_TMO], 1u); break; } } } } while (0)
; __device__ __forceinline__ void xcd_barrier(const XcdBarrier& b, const bool leader) {
;     ...
;             xb_add(&bar[XB_XGEN(b.x)], 1u);
;             asm volatile("s_waitcnt vmcnt(0)" ::: "memory");
;         } else {
;             XB_SPIN(xb_ld(&bar[XB_XGEN(b.x)]) == gen, bar);
;             __builtin_amdgcn_fence(__ATOMIC_ACQUIRE, "agent");
;             asm volatile("s_waitcnt vmcnt(0)" ::: "memory");
.LBB0_501:
	s_or_b64 exec, exec, s[6:7]
	s_mov_b64 s[14:15], exec
	v_mbcnt_lo_u32_b32 v2, s14, 0
	v_mbcnt_hi_u32_b32 v2, s15, v2
	v_cmp_eq_u32_e32 vcc, 0, v2
	s_waitcnt vmcnt(0)
	s_and_saveexec_b64 s[6:7], vcc
	s_cbranch_execz .LBB0_503
	s_bcnt1_i32_b64 s2, s[14:15]
	v_mov_b32_e32 v2, s2
.LBB0_503:
	s_or_b64 exec, exec, s[6:7]
.LBB0_504:
	s_or_b64 exec, exec, s[12:13]

; __device__ __forceinline__ unsigned xb_ld(unsigned* p)              { return __hip_atomic_load(p, __ATOMIC_RELAXED, __HIP_MEMORY_SCOPE_AGENT); }
; __device__ __forceinline__ unsigned xb_add(unsigned* p, unsigned v) { return __hip_atomic_fetch_add(p, v, __ATOMIC_RELAXED, __HIP_MEMORY_SCOPE_AGENT); }
; #define XB_SPIN(cond, bar) do { unsigned _sp = 0; while (cond) { __builtin_amdgcn_s_sleep(1); \
;     if ((++_sp & 255u) == 0u) { if (xb_ld(&(bar)[XB_TMO])) break; if (_sp > XB_SPIN_CAP) { atomicAdd(&(bar)[XB_TMO], 1u); break; } } } } while (0)
; #define LAUNDER_TID() int tid = MK_TID(); asm volatile("" : "+v"(tid)); const int lane = tid & 63, wave = __builtin_amdgcn_readfirstlane(tid >> 6)
; __device__ __forceinline__ void xcd_barrier(const XcdBarrier& b, const bool leader) {
;     ...
;             xb_add(&bar[XB_XGEN(b.x)], 1u);
;             asm volatile("s_waitcnt vmcnt(0)" ::: "memory");
;         } else {
;             XB_SPIN(xb_ld(&bar[XB_XGEN(b.x)]) == gen, bar);
;             __builtin_amdgcn_fence(__ATOMIC_ACQUIRE, "agent");
;             asm volatile("s_waitcnt vmcnt(0)" ::: "memory");
;         }
;     }
;     __syncthreads();
; __global__ void __launch_bounds__(NTHREADS, 2) fwd_megakernel(Args a) {
;     ...
;             LAUNDER_TID();
;             const int gt = bx * NTHREADS + tid, nthr = G * NTHREADS;
;             for (int v = gt; v < 32 * 4096; v += nthr) { const int pair = v >> 12, e = v & 4095, sb = pair >> 2, h = pair & 3;
;                 gla_scan_vec((unsigned char*)H, row0, (const float*)((unsigned char*)H + WS_DECB), sb * 32, 32, h, e, nullptr, out + O_GP + (size_t)((8 * grp + sb) * 4 + h) * 32768); }
.LBB0_613:
	s_or_b64 exec, exec, s[6:7]
	s_mov_b64 s[10:11], exec
	v_mbcnt_lo_u32_b32 v2, s10, 0
	v_mbcnt_hi_u32_b32 v2, s11, v2
	v_cmp_eq_u32_e32 vcc, 0, v2
	s_waitcnt vmcnt(0)
	s_and_saveexec_b64 s[6:7], vcc
	s_cbranch_execz .LBB0_615
	s_bcnt1_i32_b64 s2, s[10:11]
	v_mov_b32_e32 v2, s2
.LBB0_615:
	s_or_b64 exec, exec, s[6:7]
.LBB0_616:
	s_or_b64 exec, exec, s[4:5]
	s_load_dwordx4 s[8:11], s[90:91], 0xa8
	s_mov_b64 s[4:5], 0
	s_waitcnt lgkmcnt(0)
	s_barrier
	s_lshl_b64 s[12:13], s[4:5], 2
	v_mov_b32_e32 v2, v201
	v_readlane_b32 s0, v251, 10
	s_add_u32 s10, s8, s12
	s_mov_b32 s2, 0x20000
	v_add_u32_e32 v28, s0, v2
	v_readlane_b32 s0, v251, 39
	s_addc_u32 s11, s9, s13
	v_cmp_gt_i32_e64 s[8:9], s2, v28
	v_and_b32_e32 v29, 31, v2
	v_lshl_add_u32 v30, v2, 3, s0
	s_and_saveexec_b64 s[14:15], s[8:9]
	s_cbranch_execz .LBB0_621
	s_add_u32 s16, s10, 0xc200000
	v_readlane_b32 s0, v251, 39
	s_addc_u32 s17, s11, 0
	s_mov_b64 s[18:19], 0
	v_lshl_add_u32 v31, v2, 3, s0
	v_mov_b32_e32 v32, v28

; #define LAS __attribute__((address_space(3)))
; __device__ __forceinline__ unsigned xb_ld(unsigned* p)              { return __hip_atomic_load(p, __ATOMIC_RELAXED, __HIP_MEMORY_SCOPE_AGENT); }
; __device__ __forceinline__ unsigned xb_add(unsigned* p, unsigned v) { return __hip_atomic_fetch_add(p, v, __ATOMIC_RELAXED, __HIP_MEMORY_SCOPE_AGENT); }
; __device__ __forceinline__ bf16* ub_slot(unsigned char* ybase, int unit, int) { return (bf16*)ybase + (size_t)unit * 32768; }
; __device__ __forceinline__ void xcd_barrier(const XcdBarrier& b, const bool leader) {
;     ...
;             xb_add(&bar[XB_XGEN(b.x)], 1u);
;             asm volatile("s_waitcnt vmcnt(0)" ::: "memory");
;         } else {
;             XB_SPIN(xb_ld(&bar[XB_XGEN(b.x)]) == gen, bar);
;             __builtin_amdgcn_fence(__ATOMIC_ACQUIRE, "agent");
;             asm volatile("s_waitcnt vmcnt(0)" ::: "memory");
; __device__ __forceinline__ void gla_c_unit(LAS unsigned char* lds, const bf16* QKA, const bf16* VA, const bf16* RA, unsigned char* ws, int xnrow0, bf16* OA, int lchunk, int h, const float* gnorm, int tid) {
;     const int lane = tid & 63, w = __builtin_amdgcn_readfirstlane(tid >> 6), r32 = lane & 31, hi = lane >> 5, g16 = lane >> 4, i16 = lane & 15;
;     LAS float* SSQ = (LAS float*)(lds + G_SSQ);
;     const size_t row0 = (size_t)lchunk * 64; const int unit = lchunk * 4 + h;
; #pragma unroll
;     for (int i = 0; i < 2; ++i) { const int id = tid + 512 * i, row = id >> 4, ch = id & 15; *(LAS u32x4*)(lds + G_QD + row * GP + ch * 16) = *(const u32x4*)(QKA + (row0 + row) * 1024 + h * 128 + ch * 8); }
;     bf16x8 sf[8];
;     { const bf16* up = ub_slot(ws, unit, xnrow0) + (size_t)w * 4096 + lane * 8;
; #pragma unroll
;       for (int f = 0; f < 8; ++f) sf[f] = *(const bf16x8*)(up + f * 512); }
;     u32x2 rwv[2][4];
; #pragma unroll
;     for (int ib = 0; ib < 2; ++ib)
; #pragma unroll
;         for (int rg = 0; rg < 4; ++rg) rwv[ib][rg] = *(const u32x2*)(RA + (row0 + 32 * ib + r32) * 1024 + h * 256 + 32 * w + 4 * hi + 8 * rg);
;     f32x16 oT0, oT1;
;     { const bf16* p0 = VA + (row0 + (2 * w) * 4 + g16) * 1024 + h * 256 + i16 * 16; const bf16* p1 = p0 + 4 * 1024;
;       const u32x4 a0 = *(const u32x4*)p0, a1 = *(const u32x4*)(p0 + 8), c0 = *(const u32x4*)p1, c1 = *(const u32x4*)(p1 + 8);
.LBB0_691:
	s_or_b64 exec, exec, s[4:5]
	s_mov_b64 s[4:5], exec
	v_mbcnt_lo_u32_b32 v2, s4, 0
	v_mbcnt_hi_u32_b32 v2, s5, v2
	v_cmp_eq_u32_e32 vcc, 0, v2
	s_waitcnt vmcnt(0)
	s_and_saveexec_b64 s[6:7], vcc
	s_cbranch_execz .LBB0_693
	s_bcnt1_i32_b64 s2, s[4:5]
	v_mov_b32_e32 v2, s2
.LBB0_693:
	s_or_b64 exec, exec, s[6:7]
.LBB0_694:
	s_or_b64 exec, exec, s[8:9]
	s_load_dwordx4 s[4:7], s[90:91], 0xa8
	s_mov_b64 s[8:9], 0
	v_readlane_b32 s2, v250, 3
	s_waitcnt lgkmcnt(0)
	s_barrier
	s_add_u32 s4, s6, s8
	v_readlane_b32 s3, v250, 4
	s_addc_u32 s5, s7, s9
	v_mov_b32_e32 v59, v201
	s_andn2_b64 vcc, exec, s[2:3]
	s_cbranch_vccnz .LBB0_699
	v_lshlrev_b32_e32 v2, 4, v59
	s_add_u32 s12, s4, 0xad90000
	v_and_b32_e32 v2, 0xf0, v2
	s_addc_u32 s13, s5, 0
	v_lshl_add_u64 v[4:5], s[4:5], 0, v[2:3]
	s_mov_b64 s[10:11], 0x8c90000
	s_add_u32 s2, s4, 0xce90000
	v_lshl_add_u64 v[52:53], v[4:5], 0, s[10:11]
	v_add_u32_e32 v4, 0x200, v59
	s_addc_u32 s3, s5, 0
	v_ashrrev_i32_e32 v54, 4, v59
	s_movk_i32 s0, 0x110
	v_ashrrev_i32_e32 v56, 4, v4
	v_and_b32_e32 v58, 31, v59
	s_add_u32 s6, s4, 0x19598000
	v_mul_lo_u32 v9, v54, s0
	v_mul_lo_u32 v10, v56, s0
	v_mad_u32_u24 v11, v58, s0, 0
	v_readlane_b32 s0, v251, 57
	s_addc_u32 s7, s5, 0
	s_lshl_b64 s[8:9], s[8:9], 2
	v_lshl_add_u32 v61, v58, 2, s0
	v_readlane_b32 s0, v251, 41
	v_and_b32_e32 v6, 63, v59
	s_add_u32 s8, s0, s8
	v_readlane_b32 s0, v251, 42
	v_bfe_u32 v7, v59, 5, 1
	v_lshlrev_b32_e32 v4, 4, v6
	v_mov_b32_e32 v5, v3
	s_addc_u32 s9, s0, s9
	v_add_u32_e32 v8, 0, v2
	v_lshlrev_b32_e32 v60, 2, v7
	v_lshlrev_b32_e32 v7, 3, v7
	v_lshl_add_u64 v[66:67], s[8:9], 0, v[4:5]
	v_readlane_b32 s8, v251, 45
	v_ashrrev_i32_e32 v55, 31, v54
	v_ashrrev_i32_e32 v57, 31, v56
	v_or_b32_e32 v62, 32, v58
	v_bfe_u32 v64, v59, 4, 2
	v_cmp_gt_u32_e32 vcc, 32, v6
	v_add_u32_e32 v63, v8, v9
	v_add_u32_e32 v65, v8, v10
	v_lshlrev_b32_e32 v68, 1, v2
	v_add_u32_e32 v79, v11, v7
	s_mov_b32 s20, s8
	v_readlane_b32 s9, v251, 46
	s_branch .LBB0_697

; #define PG8_LAS __attribute__((address_space(3)))
; #define PG8_BAR __builtin_amdgcn_s_barrier()
; template <class Epi, class Sched, bool ALIGN_EPI = false, bool SP2 = false>
; __device__ __forceinline__ void gemm_phase(PG8_LAS unsigned char* lds, const Gemm g, const Sched& S, const Epi& E, const int tid_arg) {
;     int tid_l = tid_arg; asm volatile("" : "+v"(tid_l));
;     const int tid = tid_l, wid = __builtin_amdgcn_readfirstlane(tid >> 6), lane = tid & 63, wr = wid >> 2, wc = wid & 3, fr = lane & 15, fq = lane >> 4;
;     const int K = g.K, nt = K / BK;
;     unsigned voffA[2], voffB[2];
; #pragma unroll
;     for (int i = 0; i < 2; ++i) { int R, C; stage_rc(tid * 16 + i * 8192, R, C); const int Rb = Epi::PERM ? ((R & ~31) + perm32(R & 31)) : R;
;         voffA[i] = (unsigned)(R * K + C) * 2u; voffB[i] = (unsigned)(Rb * K + C) * 2u; }
;     const size_t kstep = (size_t)(BK * 2);
;     const size_t hstep = (size_t)HALF * K * 2;
;     const size_t tstep = 2 * hstep;
;     const unsigned ldsw = (unsigned)wid * 1024u;
;     const int aoff = lds_byte(wr * 64 + fr, fq * 8), boff = lds_byte(wc * 32 + fr, fq * 8);
;     ...
;     Unit cur, nxt; int ui = 0;
;     if (!S.next(0, cur)) return;
;     f32x4 acc[2][2][4][2];
; #pragma unroll
;     for (int a = 0; a < 2; ++a)
; #pragma unroll
;         for (int b = 0; b < 2; ++b)
; #pragma unroll
;             for (int m = 0; m < 4; ++m)
; #pragma unroll
;                 for (int n = 0; n < 2; ++n) acc[a][b][m][n] = (f32x4){0.f, 0.f, 0.f, 0.f};
;     bf16x8 At[4][2], B0[2][2], B1[2][2];
;     const char* cA = (const char*)g.A + (size_t)cur.pm * tstep; const char* cB = (const char*)g.Bt + (size_t)cur.pn * tstep;
;     S.a_ready(cur);
;     if constexpr (SP2) {
;         PG8_STAGE(PG8_SB(0, 0), cB, voffB); PG8_STAGE(PG8_SB(0, 1), cB + hstep, voffB); PG8_STAGE(PG8_SA(0, 0), cA, voffA); PG8_STAGE(PG8_SA(0, 1), cA + hstep, voffA);
;         if (wr == 1) PG8_BAR;
;         PG8_WAIT_V(2); PG8_BAR;
;         PG8_STAGE(PG8_SB(1, 0), cB + kstep, voffB); PG8_STAGE(PG8_SA(1, 0), cA + kstep, voffA); PG8_STAGE(PG8_SB(1, 1), cB + hstep + kstep, voffB);
;         PG8_WAIT_V(6); PG8_BAR;
;     } else {
;         PG8_STAGE(PG8_SB(0, 0), cB, voffB); PG8_STAGE(PG8_SA(0, 0), cA, voffA); PG8_STAGE(PG8_SB(0, 1), cB + hstep, voffB); PG8_STAGE(PG8_SA(0, 1), cA + hstep, voffA);
;         if (wr == 1) PG8_BAR;
;         PG8_WAIT_V(4); PG8_BAR;
.LBB0_748:
	s_or_b64 exec, exec, s[4:5]
	s_mov_b64 s[4:5], exec
	v_mbcnt_lo_u32_b32 v2, s4, 0
	v_mbcnt_hi_u32_b32 v2, s5, v2
	v_cmp_eq_u32_e32 vcc, 0, v2
	s_waitcnt vmcnt(0)
	s_and_saveexec_b64 s[6:7], vcc
	s_cbranch_execz .LBB0_750
	s_bcnt1_i32_b64 s2, s[4:5]
	v_mov_b32_e32 v2, s2
.LBB0_750:
	s_or_b64 exec, exec, s[6:7]
.LBB0_751:
	s_or_b64 exec, exec, s[8:9]
	s_load_dwordx4 s[4:7], s[90:91], 0xa8
	s_mov_b64 s[14:15], 0
	s_waitcnt lgkmcnt(0)
	s_barrier
	s_add_u32 s12, s6, s14
	s_addc_u32 s13, s7, s15
	s_add_u32 s16, s12, 0x15290000
	v_readlane_b32 s2, v251, 63
	s_addc_u32 s17, s13, 0
	v_readlane_b32 s3, v250, 0
	s_add_u32 s18, s12, 0x8c90000
	v_mov_b32_e32 v10, v201
	v_cndmask_b32_e64 v2, 0, 1, s[2:3]
	s_addc_u32 s19, s13, 0
	v_cmp_ne_u32_e64 s[8:9], 1, v2
	s_andn2_b64 vcc, exec, s[2:3]
	v_readfirstlane_b32 s2, v10
	s_cbranch_vccnz .LBB0_771
	v_lshlrev_b32_e32 v2, 4, v10
	v_add_u32_e32 v5, 0x2000, v2
	v_ashrrev_i32_e32 v4, 31, v5
	v_lshrrev_b32_e32 v4, 22, v4
	v_add_u32_e32 v4, v5, v4
	v_ashrrev_i32_e32 v4, 10, v4
	v_mul_i32_i24_e32 v6, 0x400, v4
	v_sub_u32_e32 v5, v5, v6
	v_lshrrev_b32_e32 v6, 4, v5
	v_bitop3_b32 v6, v6, v5, 32 bitop3:0x6c
	v_ashrrev_i32_e32 v5, 31, v6
	v_lshrrev_b32_e32 v5, 26, v5
	v_add_u32_e32 v7, v6, v5
	v_lshlrev_b32_e32 v8, 3, v4
	v_ashrrev_i32_e32 v5, 6, v7
	v_and_b32_e32 v8, -16, v8
	v_add_u32_e32 v8, v5, v8
	v_and_b32_e32 v9, 3, v5
	s_mov_b32 s0, 0x1fffe0
	v_lshrrev_b32_e32 v11, 2, v8
	v_lshlrev_b32_e32 v12, 1, v8
	v_and_b32_e32 v7, 0xc0, v7
	v_and_or_b32 v9, v8, s0, v9
	v_and_b32_e32 v11, 4, v11
	v_and_b32_e32 v12, 24, v12
	v_sub_u32_e32 v6, v6, v7
	v_or3_b32 v9, v9, v11, v12
	v_lshlrev_b32_e32 v11, 5, v4
	v_ashrrev_i16_sdwa v6, v204, sext(v6) dst_sel:DWORD dst_unused:UNUSED_PAD src0_sel:DWORD src1_sel:BYTE_0
	v_and_b32_e32 v11, 32, v11
	v_bfe_i32 v6, v6, 0, 16
	v_add_lshl_u32 v7, v11, v6, 1
	v_lshl_add_u32 v132, v9, 11, v7
	v_lshl_add_u32 v134, v8, 11, v7
	v_bfe_i32 v7, v10, 27, 1
	v_lshrrev_b32_e32 v7, 22, v7
	v_add_u32_e32 v7, v2, v7
	v_and_b32_e32 v7, 0xfffffc00, v7
	v_sub_u32_e32 v2, v2, v7
	v_lshrrev_b32_e32 v7, 4, v2
	v_ashrrev_i32_e32 v8, 31, v10
	v_bitop3_b32 v2, v7, v2, 32 bitop3:0x6c
	v_lshrrev_b32_e32 v8, 26, v8
	v_ashrrev_i32_e32 v7, 31, v2
	v_add_u32_e32 v8, v10, v8
	v_lshrrev_b32_e32 v7, 26, v7
	v_ashrrev_i32_e32 v8, 6, v8
	v_add_u32_e32 v9, v2, v7
	v_lshlrev_b32_e32 v11, 3, v8
	s_add_u32 s3, s12, 0x19598000
	v_ashrrev_i32_e32 v7, 6, v9
	v_and_b32_e32 v11, -16, v11
	s_addc_u32 s6, s13, 0
	v_add_u32_e32 v11, v7, v11
	s_add_u32 s7, s12, 0x2100000
	v_and_b32_e32 v12, 3, v7
	v_lshrrev_b32_e32 v13, 2, v11
	v_lshlrev_b32_e32 v14, 1, v11
	v_and_b32_e32 v9, 0xc0, v9
	s_addc_u32 s38, s13, 0
	s_ashr_i32 s10, s2, 6
	v_and_or_b32 v12, v11, s0, v12
	v_and_b32_e32 v13, 4, v13
	v_and_b32_e32 v14, 24, v14
	v_sub_u32_e32 v2, v2, v9
	s_ashr_i32 s11, s2, 8
	s_lshl_b32 s39, s10, 10
	v_or3_b32 v12, v12, v13, v14
	v_lshlrev_b32_e32 v13, 5, v8
	v_ashrrev_i16_sdwa v2, v204, sext(v2) dst_sel:DWORD dst_unused:UNUSED_PAD src0_sel:DWORD src1_sel:BYTE_0
	v_readlane_b32 s4, v251, 21
	v_and_b32_e32 v13, 32, v13
	v_bfe_i32 v9, v2, 0, 16
	v_readlane_b32 s5, v251, 22
	s_add_u32 s34, s7, s4
	v_add_lshl_u32 v13, v13, v9, 1
	s_addc_u32 s35, s38, s5
	s_add_i32 s40, s39, 0
	v_lshl_add_u32 v2, v12, 11, v13
	s_add_i32 m0, s40, 0x10000
	v_lshl_add_u32 v136, v11, 11, v13
	global_load_lds_dwordx4 v2, s[34:35]
	s_add_i32 m0, s40, 0x12000
	s_add_u32 s4, s34, 0x40000
	global_load_lds_dwordx4 v132, s[34:35]
	s_addc_u32 s5, s35, 0
	s_add_i32 m0, s40, 0x14000
	s_nop 0
	global_load_lds_dwordx4 v2, s[4:5]
	s_add_i32 m0, s40, 0x16000
	s_nop 0
	global_load_lds_dwordx4 v132, s[4:5]
	v_readlane_b32 s4, v251, 19
	v_readlane_b32 s5, v251, 20
	s_add_u32 s4, s3, s4
	s_addc_u32 s5, s6, s5
	s_add_i32 s41, s40, 0x2000
	s_mov_b32 m0, s40
	s_add_u32 s20, s4, 0x40000
	global_load_lds_dwordx4 v136, s[4:5]
	s_mov_b32 m0, s41
	s_addc_u32 s21, s5, 0
	s_add_i32 s42, s40, 0x4000
	global_load_lds_dwordx4 v134, s[4:5]
	s_mov_b32 m0, s42
	s_add_i32 s43, s40, 0x6000
	global_load_lds_dwordx4 v136, s[20:21]
	s_mov_b32 m0, s43
	s_cmp_eq_u32 s11, 1
	global_load_lds_dwordx4 v134, s[20:21]
	s_cselect_b64 s[20:21], -1, 0
	s_cmp_lg_u32 s11, 1
	s_cbranch_scc1 .LBB0_754
	s_barrier

; template <class Epi, class Sched, bool ALIGN_EPI = false, bool SP2 = false>
; __device__ __forceinline__ void gemm_phase(PG8_LAS unsigned char* lds, const Gemm g, const Sched& S, const Epi& E, const int tid_arg) {
;     ...
;         const bool has_next = S.next(ui + 1, nxt);
;         const char* nA = has_next ? (const char*)g.A + (size_t)nxt.pm * tstep : cA; const char* nB = has_next ? (const char*)g.Bt + (size_t)nxt.pn * tstep : cB;
;     ...
;         for (int a = 0; a < 2; ++a)
; #pragma unroll
;             for (int b = 0; b < 2; ++b)
; #pragma unroll
;                 for (int m = 0; m < 4; ++m)
; #pragma unroll
;                     for (int n = 0; n < 2; ++n) acc[a][b][m][n] = (f32x4){0.f, 0.f, 0.f, 0.f};
;         cur = nxt; cA = nA; cB = nB; ++ui;
.LBB0_763:
	s_ashr_i32 s27, s26, 31
	s_lshl_b64 s[28:29], s[26:27], 19
	s_add_u32 s28, s3, s28
	s_addc_u32 s29, s6, s29
	s_and_b64 s[30:31], s[10:11], exec
	s_cselect_b32 s27, s29, s5
	s_cselect_b32 s48, s28, s4
	s_ashr_i32 s25, s24, 31
	s_lshl_b64 s[30:31], s[24:25], 19
	s_add_u32 s30, s7, s30
	s_addc_u32 s31, s38, s31
	s_and_b64 s[36:37], s[10:11], exec
	s_cselect_b32 s25, s31, s35
	s_cselect_b32 s49, s30, s34
	s_add_u32 s4, s4, 0x40080
	s_addc_u32 s5, s5, 0
	s_add_u32 s50, s34, 0x100
	v_mov_b32_e32 v4, 0
	s_addc_u32 s51, s35, 0
	s_mov_b32 s52, -2
	v_mov_b32_e32 v5, v4
	v_mov_b32_e32 v6, v4
	v_mov_b32_e32 v7, v4
	v_mov_b32_e32 v8, v4
	v_mov_b32_e32 v9, v4
	v_mov_b32_e32 v10, v4
	v_mov_b32_e32 v11, v4
	v_mov_b32_e32 v20, v4
	v_mov_b32_e32 v21, v4
	v_mov_b32_e32 v22, v4
	v_mov_b32_e32 v23, v4
	v_mov_b32_e32 v24, v4
	v_mov_b32_e32 v25, v4
	v_mov_b32_e32 v26, v4
	v_mov_b32_e32 v27, v4
	v_mov_b32_e32 v36, v4
	v_mov_b32_e32 v37, v4
	v_mov_b32_e32 v38, v4
	v_mov_b32_e32 v39, v4
	v_mov_b32_e32 v40, v4
	v_mov_b32_e32 v41, v4
	v_mov_b32_e32 v42, v4
	v_mov_b32_e32 v43, v4
	v_mov_b32_e32 v52, v4
	v_mov_b32_e32 v53, v4
	v_mov_b32_e32 v54, v4
	v_mov_b32_e32 v55, v4
	v_mov_b32_e32 v56, v4
	v_mov_b32_e32 v57, v4
	v_mov_b32_e32 v58, v4
	v_mov_b32_e32 v59, v4
	v_mov_b32_e32 v12, v4
	v_mov_b32_e32 v13, v4
	v_mov_b32_e32 v14, v4
	v_mov_b32_e32 v15, v4
	v_mov_b32_e32 v16, v4
	v_mov_b32_e32 v17, v4
	v_mov_b32_e32 v18, v4
	v_mov_b32_e32 v19, v4
	v_mov_b32_e32 v28, v4
	v_mov_b32_e32 v29, v4
	v_mov_b32_e32 v30, v4
	v_mov_b32_e32 v31, v4
	v_mov_b32_e32 v32, v4
	v_mov_b32_e32 v33, v4
	v_mov_b32_e32 v34, v4
	v_mov_b32_e32 v35, v4
	v_mov_b32_e32 v44, v4
	v_mov_b32_e32 v45, v4
	v_mov_b32_e32 v46, v4
	v_mov_b32_e32 v47, v4
	v_mov_b32_e32 v48, v4
	v_mov_b32_e32 v49, v4
	v_mov_b32_e32 v50, v4
	v_mov_b32_e32 v51, v4
	v_mov_b32_e32 v60, v4
	v_mov_b32_e32 v61, v4
	v_mov_b32_e32 v62, v4
	v_mov_b32_e32 v63, v4
	v_mov_b32_e32 v64, v4
	v_mov_b32_e32 v65, v4
	v_mov_b32_e32 v66, v4
	v_mov_b32_e32 v67, v4
	v_mov_b32_e32 v68, v4
	v_mov_b32_e32 v69, v4
	v_mov_b32_e32 v70, v4
	v_mov_b32_e32 v71, v4
	v_mov_b32_e32 v72, v4
	v_mov_b32_e32 v73, v4
	v_mov_b32_e32 v74, v4
	v_mov_b32_e32 v75, v4
	v_mov_b32_e32 v84, v4
	v_mov_b32_e32 v85, v4
	v_mov_b32_e32 v86, v4
	v_mov_b32_e32 v87, v4
	v_mov_b32_e32 v88, v4
	v_mov_b32_e32 v89, v4
	v_mov_b32_e32 v90, v4
	v_mov_b32_e32 v91, v4
	v_mov_b32_e32 v100, v4
	v_mov_b32_e32 v101, v4
	v_mov_b32_e32 v102, v4
	v_mov_b32_e32 v103, v4
	v_mov_b32_e32 v104, v4
	v_mov_b32_e32 v105, v4
	v_mov_b32_e32 v106, v4
	v_mov_b32_e32 v107, v4
	v_mov_b32_e32 v116, v4
	v_mov_b32_e32 v117, v4
	v_mov_b32_e32 v118, v4
	v_mov_b32_e32 v119, v4
	s_waitcnt vmcnt(0)
	v_mov_b32_e32 v120, v4
	v_mov_b32_e32 v121, v4
	v_mov_b32_e32 v122, v4
	v_mov_b32_e32 v123, v4
	v_mov_b32_e32 v76, v4
	v_mov_b32_e32 v77, v4
	v_mov_b32_e32 v78, v4
	v_mov_b32_e32 v79, v4
	v_mov_b32_e32 v80, v4
	v_mov_b32_e32 v81, v4
	v_mov_b32_e32 v82, v4
	v_mov_b32_e32 v83, v4
	v_mov_b32_e32 v92, v4
	v_mov_b32_e32 v93, v4
	v_mov_b32_e32 v94, v4
	v_mov_b32_e32 v95, v4
	v_mov_b32_e32 v96, v4
	v_mov_b32_e32 v97, v4
	v_mov_b32_e32 v98, v4
	v_mov_b32_e32 v99, v4
	v_mov_b32_e32 v108, v4
	v_mov_b32_e32 v109, v4
	v_mov_b32_e32 v110, v4
	v_mov_b32_e32 v111, v4
	v_mov_b32_e32 v112, v4
	v_mov_b32_e32 v113, v4
	v_mov_b32_e32 v114, v4
	v_mov_b32_e32 v115, v4
	v_mov_b32_e32 v124, v4
	v_mov_b32_e32 v125, v4
	v_mov_b32_e32 v126, v4
	v_mov_b32_e32 v127, v4
	v_mov_b32_e32 v128, v4
	v_mov_b32_e32 v129, v4
	v_mov_b32_e32 v130, v4
	v_mov_b32_e32 v131, v4
	s_nop 0
	s_nop 0
	s_nop 0
	s_nop 0
	s_nop 0
	s_nop 0
	s_nop 0
	s_nop 0
	s_nop 0
	s_nop 0
	s_nop 0
	s_nop 0
	s_nop 0
	s_nop 0
	s_nop 0
	s_nop 0
	s_nop 0
	s_nop 0
	s_nop 0
	s_nop 0
	s_nop 0
	s_nop 0
	s_nop 0
	s_nop 0

; #define PG8_LAS __attribute__((address_space(3)))
; #define PG8_BAR __builtin_amdgcn_s_barrier()
; template <class Epi, class Sched, bool ALIGN_EPI = false, bool SP2 = false>
; __device__ __forceinline__ void gemm_phase(PG8_LAS unsigned char* lds, const Gemm g, const Sched& S, const Epi& E, const int tid_arg) {
;     int tid_l = tid_arg; asm volatile("" : "+v"(tid_l));
;     const int tid = tid_l, wid = __builtin_amdgcn_readfirstlane(tid >> 6), lane = tid & 63, wr = wid >> 2, wc = wid & 3, fr = lane & 15, fq = lane >> 4;
;     const int K = g.K, nt = K / BK;
;     unsigned voffA[2], voffB[2];
; #pragma unroll
;     for (int i = 0; i < 2; ++i) { int R, C; stage_rc(tid * 16 + i * 8192, R, C); const int Rb = Epi::PERM ? ((R & ~31) + perm32(R & 31)) : R;
;         voffA[i] = (unsigned)(R * K + C) * 2u; voffB[i] = (unsigned)(Rb * K + C) * 2u; }
;     const size_t kstep = (size_t)(BK * 2);
;     const size_t hstep = (size_t)HALF * K * 2;
;     const size_t tstep = 2 * hstep;
;     const unsigned ldsw = (unsigned)wid * 1024u;
;     const int aoff = lds_byte(wr * 64 + fr, fq * 8), boff = lds_byte(wc * 32 + fr, fq * 8);
;     ...
;     Unit cur, nxt; int ui = 0;
;     if (!S.next(0, cur)) return;
;     f32x4 acc[2][2][4][2];
; #pragma unroll
;     for (int a = 0; a < 2; ++a)
; #pragma unroll
;         for (int b = 0; b < 2; ++b)
; #pragma unroll
;             for (int m = 0; m < 4; ++m)
; #pragma unroll
;                 for (int n = 0; n < 2; ++n) acc[a][b][m][n] = (f32x4){0.f, 0.f, 0.f, 0.f};
;     bf16x8 At[4][2], B0[2][2], B1[2][2];
;     const char* cA = (const char*)g.A + (size_t)cur.pm * tstep; const char* cB = (const char*)g.Bt + (size_t)cur.pn * tstep;
;     S.a_ready(cur);
;     if constexpr (SP2) {
;         PG8_STAGE(PG8_SB(0, 0), cB, voffB); PG8_STAGE(PG8_SB(0, 1), cB + hstep, voffB); PG8_STAGE(PG8_SA(0, 0), cA, voffA); PG8_STAGE(PG8_SA(0, 1), cA + hstep, voffA);
;         if (wr == 1) PG8_BAR;
;         PG8_WAIT_V(2); PG8_BAR;
;         PG8_STAGE(PG8_SB(1, 0), cB + kstep, voffB); PG8_STAGE(PG8_SA(1, 0), cA + kstep, voffA); PG8_STAGE(PG8_SB(1, 1), cB + hstep + kstep, voffB);
;         PG8_WAIT_V(6); PG8_BAR;
;     } else {
;         PG8_STAGE(PG8_SB(0, 0), cB, voffB); PG8_STAGE(PG8_SA(0, 0), cA, voffA); PG8_STAGE(PG8_SB(0, 1), cB + hstep, voffB); PG8_STAGE(PG8_SA(0, 1), cA + hstep, voffA);
;         if (wr == 1) PG8_BAR;
;         PG8_WAIT_V(4); PG8_BAR;
.LBB0_852:
	s_or_b64 exec, exec, s[6:7]
	s_mov_b64 s[12:13], exec
	v_mbcnt_lo_u32_b32 v2, s12, 0
	v_mbcnt_hi_u32_b32 v2, s13, v2
	v_cmp_eq_u32_e32 vcc, 0, v2
	s_waitcnt vmcnt(0)
	s_and_saveexec_b64 s[6:7], vcc
	s_cbranch_execz .LBB0_854
	s_bcnt1_i32_b64 s2, s[12:13]
	v_mov_b32_e32 v2, s2
.LBB0_854:
	s_or_b64 exec, exec, s[6:7]
.LBB0_855:
	s_or_b64 exec, exec, s[4:5]
	s_load_dwordx4 s[12:15], s[90:91], 0xa8
	s_mov_b64 s[4:5], 0
	s_waitcnt lgkmcnt(0)
	s_barrier
	s_add_u32 s18, s14, s4
	s_addc_u32 s19, s15, s5
	s_lshl_b64 s[20:21], s[4:5], 2
	s_add_u32 s3, s12, s20
	v_mov_b32_e32 v18, v201
	s_addc_u32 s46, s13, s21
	s_and_b64 vcc, exec, s[8:9]
	v_readfirstlane_b32 s6, v18
	s_cbranch_vccnz .LBB0_1004
	v_lshlrev_b32_e32 v2, 4, v18
	v_add_u32_e32 v4, 0x2000, v2
	v_ashrrev_i32_e32 v5, 31, v4
	v_lshrrev_b32_e32 v5, 22, v5
	v_add_u32_e32 v5, v4, v5
	v_ashrrev_i32_e32 v12, 10, v5
	v_mul_i32_i24_e32 v5, 0x400, v12
	v_sub_u32_e32 v4, v4, v5
	v_lshrrev_b32_e32 v5, 4, v4
	v_bitop3_b32 v4, v5, v4, 32 bitop3:0x6c
	v_ashrrev_i32_e32 v5, 31, v4
	v_lshrrev_b32_e32 v5, 26, v5
	v_add_u32_e32 v5, v4, v5
	v_lshlrev_b32_e32 v6, 3, v12
	v_ashrrev_i32_e32 v13, 6, v5
	v_and_b32_e32 v6, -16, v6
	v_add_u32_e32 v6, v13, v6
	v_and_b32_e32 v7, 3, v13
	s_mov_b32 s0, 0x1fffe0
	v_lshrrev_b32_e32 v8, 2, v6
	v_lshlrev_b32_e32 v9, 1, v6
	v_and_b32_e32 v5, 0xc0, v5
	v_and_or_b32 v7, v6, s0, v7
	v_and_b32_e32 v8, 4, v8
	v_and_b32_e32 v9, 24, v9
	v_sub_u32_e32 v4, v4, v5
	v_or3_b32 v7, v7, v8, v9
	v_lshlrev_b32_e32 v8, 5, v12
	v_ashrrev_i16_sdwa v4, v204, sext(v4) dst_sel:DWORD dst_unused:UNUSED_PAD src0_sel:DWORD src1_sel:BYTE_0
	v_and_b32_e32 v8, 32, v8
	v_bfe_i32 v14, v4, 0, 16
	v_add_lshl_u32 v4, v8, v14, 1
	v_lshl_add_u32 v146, v7, 11, v4
	v_lshl_add_u32 v148, v6, 11, v4
	v_bfe_i32 v4, v18, 27, 1
	v_lshrrev_b32_e32 v4, 22, v4
	v_add_u32_e32 v4, v2, v4
	v_and_b32_e32 v4, 0xfffffc00, v4
	v_sub_u32_e32 v2, v2, v4
	v_lshrrev_b32_e32 v4, 4, v2
	v_ashrrev_i32_e32 v5, 31, v18
	v_bitop3_b32 v2, v4, v2, 32 bitop3:0x6c
	v_lshrrev_b32_e32 v5, 26, v5
	v_ashrrev_i32_e32 v4, 31, v2
	v_add_u32_e32 v5, v18, v5
	v_lshrrev_b32_e32 v4, 26, v4
	v_ashrrev_i32_e32 v16, 6, v5
	v_add_u32_e32 v4, v2, v4
	v_lshlrev_b32_e32 v5, 3, v16
	s_add_u32 s2, s3, 0x4800000
	v_ashrrev_i32_e32 v15, 6, v4
	v_and_b32_e32 v5, -16, v5
	s_addc_u32 s47, s46, 0
	v_add_u32_e32 v5, v15, v5
	s_add_u32 s48, s18, 0x2500000
	v_and_b32_e32 v6, 3, v15
	v_lshrrev_b32_e32 v7, 2, v5
	v_lshlrev_b32_e32 v8, 1, v5
	v_and_b32_e32 v4, 0xc0, v4
	s_addc_u32 s49, s19, 0
	s_ashr_i32 s12, s6, 6
	v_and_or_b32 v6, v5, s0, v6
	v_and_b32_e32 v7, 4, v7
	v_and_b32_e32 v8, 24, v8
	v_sub_u32_e32 v2, v2, v4
	s_ashr_i32 s7, s6, 8
	s_lshl_b32 s50, s12, 10
	v_or3_b32 v6, v6, v7, v8
	v_lshlrev_b32_e32 v7, 5, v16
	v_ashrrev_i16_sdwa v2, v204, sext(v2) dst_sel:DWORD dst_unused:UNUSED_PAD src0_sel:DWORD src1_sel:BYTE_0
	v_readlane_b32 s14, v251, 21
	v_and_b32_e32 v7, 32, v7
	v_bfe_i32 v17, v2, 0, 16
	v_readlane_b32 s15, v251, 22
	s_add_u32 s42, s48, s14
	v_add_lshl_u32 v4, v7, v17, 1
	s_addc_u32 s43, s49, s15
	s_add_i32 s51, s50, 0
	v_lshl_add_u32 v2, v6, 11, v4
	s_add_i32 m0, s51, 0x10000
	v_lshl_add_u32 v150, v5, 11, v4
	global_load_lds_dwordx4 v2, s[42:43]
	s_add_i32 m0, s51, 0x12000
	s_add_u32 s14, s42, 0x40000
	global_load_lds_dwordx4 v146, s[42:43]
	s_addc_u32 s15, s43, 0
	s_add_i32 m0, s51, 0x14000
	v_mov_b32_e32 v147, v3
	global_load_lds_dwordx4 v2, s[14:15]
	s_add_i32 m0, s51, 0x16000
	v_mov_b32_e32 v151, v3
	global_load_lds_dwordx4 v146, s[14:15]
	v_readlane_b32 s14, v251, 19
	v_readlane_b32 s15, v251, 20
	s_add_u32 s16, s2, s14
	s_addc_u32 s17, s47, s15
	s_add_i32 s52, s51, 0x2000
	s_mov_b32 m0, s51
	s_add_u32 s14, s16, 0x40000
	global_load_lds_dwordx4 v150, s[16:17]
	s_mov_b32 m0, s52
	s_addc_u32 s15, s17, 0
	s_add_i32 s53, s51, 0x4000
	global_load_lds_dwordx4 v148, s[16:17]
	s_mov_b32 m0, s53
	s_add_i32 s54, s51, 0x6000
	global_load_lds_dwordx4 v150, s[14:15]
	s_mov_b32 m0, s54
	v_mov_b32_e32 v149, v3
	global_load_lds_dwordx4 v148, s[14:15]
	s_cmp_eq_u32 s7, 1
	v_lshl_add_u64 v[10:11], s[42:43], 0, v[2:3]
	v_lshl_add_u64 v[8:9], s[42:43], 0, v[146:147]
	v_lshl_add_u64 v[4:5], s[16:17], 0, v[150:151]
	s_cselect_b64 s[22:23], -1, 0
	s_cmp_lg_u32 s7, 1
	v_lshl_add_u64 v[6:7], s[16:17], 0, v[148:149]
	s_cbranch_scc1 .LBB0_858
	s_barrier

; template <class Epi, class Sched, bool ALIGN_EPI = false, bool SP2 = false>
; __device__ __forceinline__ void gemm_phase(PG8_LAS unsigned char* lds, const Gemm g, const Sched& S, const Epi& E, const int tid_arg) {
;     ...
;         for (int a = 0; a < 2; ++a)
; #pragma unroll
;             for (int b = 0; b < 2; ++b)
; #pragma unroll
;                 for (int m = 0; m < 4; ++m)
; #pragma unroll
;                     for (int n = 0; n < 2; ++n) acc[a][b][m][n] = (f32x4){0.f, 0.f, 0.f, 0.f};
;         cur = nxt; cA = nA; cB = nB; ++ui;
.LBB0_867:
	s_ashr_i32 s35, s34, 31
	s_lshl_b64 s[36:37], s[34:35], 19
	s_add_u32 s36, s2, s36
	s_addc_u32 s37, s47, s37
	s_and_b64 s[38:39], s[14:15], exec
	s_cselect_b32 s7, s37, s17
	s_cselect_b32 s35, s36, s16
	s_ashr_i32 s31, s30, 31
	s_lshl_b64 s[38:39], s[30:31], 19
	s_add_u32 s38, s48, s38
	s_addc_u32 s39, s49, s39
	s_and_b64 s[44:45], s[14:15], exec
	s_cselect_b32 s31, s39, s43
	s_cselect_b32 s41, s38, s42
	s_add_u32 s16, s16, 0x40080
	s_addc_u32 s17, s17, 0
	s_add_u32 s59, s42, 0x100
	v_mov_b32_e32 v4, 0
	s_addc_u32 s60, s43, 0
	s_mov_b32 s61, -2
	s_waitcnt lgkmcnt(0)
	v_mov_b32_e32 v5, v4
	v_mov_b32_e32 v6, v4
	v_mov_b32_e32 v7, v4
	v_mov_b32_e32 v8, v4
	v_mov_b32_e32 v9, v4
	v_mov_b32_e32 v10, v4
	v_mov_b32_e32 v11, v4
	v_mov_b32_e32 v20, v4
	v_mov_b32_e32 v21, v4
	v_mov_b32_e32 v22, v4
	v_mov_b32_e32 v23, v4
	v_mov_b32_e32 v24, v4
	v_mov_b32_e32 v25, v4
	v_mov_b32_e32 v26, v4
	v_mov_b32_e32 v27, v4
	v_mov_b32_e32 v36, v4
	v_mov_b32_e32 v37, v4
	v_mov_b32_e32 v38, v4
	v_mov_b32_e32 v39, v4
	v_mov_b32_e32 v40, v4
	v_mov_b32_e32 v41, v4
	v_mov_b32_e32 v42, v4
	v_mov_b32_e32 v43, v4
	v_mov_b32_e32 v52, v4
	v_mov_b32_e32 v53, v4
	v_mov_b32_e32 v54, v4
	v_mov_b32_e32 v55, v4
	v_mov_b32_e32 v56, v4
	v_mov_b32_e32 v57, v4
	v_mov_b32_e32 v58, v4
	v_mov_b32_e32 v59, v4
	v_mov_b32_e32 v12, v4
	v_mov_b32_e32 v13, v4
	v_mov_b32_e32 v14, v4
	v_mov_b32_e32 v15, v4
	v_mov_b32_e32 v16, v4
	v_mov_b32_e32 v17, v4
	v_mov_b32_e32 v18, v4
	v_mov_b32_e32 v19, v4
	v_mov_b32_e32 v28, v4
	v_mov_b32_e32 v29, v4
	v_mov_b32_e32 v30, v4
	v_mov_b32_e32 v31, v4
	v_mov_b32_e32 v32, v4
	v_mov_b32_e32 v33, v4
	v_mov_b32_e32 v34, v4
	v_mov_b32_e32 v35, v4
	v_mov_b32_e32 v44, v4
	v_mov_b32_e32 v45, v4
	v_mov_b32_e32 v46, v4
	v_mov_b32_e32 v47, v4
	v_mov_b32_e32 v48, v4
	v_mov_b32_e32 v49, v4
	v_mov_b32_e32 v50, v4
	v_mov_b32_e32 v51, v4
	v_mov_b32_e32 v60, v4
	v_mov_b32_e32 v61, v4
	v_mov_b32_e32 v62, v4
	v_mov_b32_e32 v63, v4
	v_mov_b32_e32 v64, v4
	v_mov_b32_e32 v65, v4
	v_mov_b32_e32 v66, v4
	v_mov_b32_e32 v67, v4
	v_mov_b32_e32 v68, v4
	v_mov_b32_e32 v69, v4
	v_mov_b32_e32 v70, v4
	v_mov_b32_e32 v71, v4
	v_mov_b32_e32 v72, v4
	v_mov_b32_e32 v73, v4
	v_mov_b32_e32 v74, v4
	v_mov_b32_e32 v75, v4
	v_mov_b32_e32 v84, v4
	v_mov_b32_e32 v85, v4
	v_mov_b32_e32 v86, v4
	v_mov_b32_e32 v87, v4
	v_mov_b32_e32 v88, v4
	v_mov_b32_e32 v89, v4
	v_mov_b32_e32 v90, v4
	v_mov_b32_e32 v91, v4
	v_mov_b32_e32 v100, v4
	v_mov_b32_e32 v101, v4
	v_mov_b32_e32 v102, v4
	v_mov_b32_e32 v103, v4
	v_mov_b32_e32 v104, v4
	v_mov_b32_e32 v105, v4
	v_mov_b32_e32 v106, v4
	v_mov_b32_e32 v107, v4
	v_mov_b32_e32 v116, v4
	v_mov_b32_e32 v117, v4
	v_mov_b32_e32 v118, v4
	v_mov_b32_e32 v119, v4
	s_waitcnt vmcnt(0)
	v_mov_b32_e32 v120, v4
	v_mov_b32_e32 v121, v4
	v_mov_b32_e32 v122, v4
	v_mov_b32_e32 v123, v4
	v_mov_b32_e32 v76, v4
	v_mov_b32_e32 v77, v4
	v_mov_b32_e32 v78, v4
	v_mov_b32_e32 v79, v4
	v_mov_b32_e32 v80, v4
	v_mov_b32_e32 v81, v4
	v_mov_b32_e32 v82, v4
	v_mov_b32_e32 v83, v4
	v_mov_b32_e32 v92, v4
	v_mov_b32_e32 v93, v4
	v_mov_b32_e32 v94, v4
	v_mov_b32_e32 v95, v4
	v_mov_b32_e32 v96, v4
	v_mov_b32_e32 v97, v4
	v_mov_b32_e32 v98, v4
	v_mov_b32_e32 v99, v4
	v_mov_b32_e32 v108, v4
	v_mov_b32_e32 v109, v4
	v_mov_b32_e32 v110, v4
	v_mov_b32_e32 v111, v4
	v_mov_b32_e32 v112, v4
	v_mov_b32_e32 v113, v4
	v_mov_b32_e32 v114, v4
	v_mov_b32_e32 v115, v4
	v_mov_b32_e32 v124, v4
	v_mov_b32_e32 v125, v4
	v_mov_b32_e32 v126, v4
	v_mov_b32_e32 v127, v4
	v_mov_b32_e32 v128, v4
	v_mov_b32_e32 v129, v4
	v_mov_b32_e32 v130, v4
	v_mov_b32_e32 v131, v4
	s_nop 0
	s_nop 0
	s_nop 0
	s_nop 0

; __device__ __forceinline__ unsigned xb_ld(unsigned* p)              { return __hip_atomic_load(p, __ATOMIC_RELAXED, __HIP_MEMORY_SCOPE_AGENT); }
; __device__ __forceinline__ unsigned xb_add(unsigned* p, unsigned v) { return __hip_atomic_fetch_add(p, v, __ATOMIC_RELAXED, __HIP_MEMORY_SCOPE_AGENT); }
; #define XB_SPIN(cond, bar) do { unsigned _sp = 0; while (cond) { __builtin_amdgcn_s_sleep(1); \
;     if ((++_sp & 255u) == 0u) { if (xb_ld(&(bar)[XB_TMO])) break; if (_sp > XB_SPIN_CAP) { atomicAdd(&(bar)[XB_TMO], 1u); break; } } } } while (0)
; __device__ __forceinline__ void xcd_barrier(const XcdBarrier& b, const bool leader) {
;     ...
;             xb_add(&bar[XB_XGEN(b.x)], 1u);
;             asm volatile("s_waitcnt vmcnt(0)" ::: "memory");
;         } else {
;             XB_SPIN(xb_ld(&bar[XB_XGEN(b.x)]) == gen, bar);
;             __builtin_amdgcn_fence(__ATOMIC_ACQUIRE, "agent");
;             asm volatile("s_waitcnt vmcnt(0)" ::: "memory");
.LBB0_1061:
	s_or_b64 exec, exec, s[6:7]
	s_mov_b64 s[12:13], exec
	v_mbcnt_lo_u32_b32 v2, s12, 0
	v_mbcnt_hi_u32_b32 v2, s13, v2
	v_cmp_eq_u32_e32 vcc, 0, v2
	s_waitcnt vmcnt(0)
	s_and_saveexec_b64 s[6:7], vcc
	s_cbranch_execz .LBB0_345
	s_bcnt1_i32_b64 s2, s[12:13]
	v_mov_b32_e32 v2, s2
	s_branch .LBB0_345

; template <class Epi, class Sched, bool ALIGN_EPI = false, bool SP2 = false>
; __device__ __forceinline__ void gemm_phase(PG8_LAS unsigned char* lds, const Gemm g, const Sched& S, const Epi& E, const int tid_arg) {
;     ...
;         for (int a = 0; a < 2; ++a)
; #pragma unroll
;             for (int b = 0; b < 2; ++b)
; #pragma unroll
;                 for (int m = 0; m < 4; ++m)
; #pragma unroll
;                     for (int n = 0; n < 2; ++n) acc[a][b][m][n] = (f32x4){0.f, 0.f, 0.f, 0.f};
;         cur = nxt; cA = nA; cB = nB; ++ui;
.LBB0_1079:
	s_ashr_i32 s21, s20, 31
	s_lshl_b64 s[22:23], s[20:21], 19
	s_add_u32 s22, s0, s22
	s_addc_u32 s23, s1, s23
	s_and_b64 s[24:25], s[10:11], exec
	s_cselect_b32 s21, s23, s29
	s_cselect_b32 s47, s22, s28
	s_ashr_i32 s17, s16, 31
	s_lshl_b64 s[24:25], s[16:17], 19
	s_add_u32 s24, s2, s24
	s_addc_u32 s25, s3, s25
	s_and_b64 s[34:35], s[10:11], exec
	s_cselect_b32 s17, s25, s31
	s_cselect_b32 s48, s24, s30
	s_add_u32 s28, s28, 0x40080
	s_addc_u32 s29, s29, 0
	s_add_u32 s49, s30, 0x100
	v_mov_b32_e32 v2, 0
	s_addc_u32 s50, s31, 0
	s_mov_b32 s51, -2
	v_mov_b32_e32 v3, v2
	v_mov_b32_e32 v4, v2
	v_mov_b32_e32 v5, v2
	v_mov_b32_e32 v6, v2
	v_mov_b32_e32 v7, v2
	v_mov_b32_e32 v8, v2
	v_mov_b32_e32 v9, v2
	v_mov_b32_e32 v18, v2
	v_mov_b32_e32 v19, v2
	v_mov_b32_e32 v20, v2
	v_mov_b32_e32 v21, v2
	v_mov_b32_e32 v22, v2
	v_mov_b32_e32 v23, v2
	v_mov_b32_e32 v24, v2
	v_mov_b32_e32 v25, v2
	v_mov_b32_e32 v34, v2
	v_mov_b32_e32 v35, v2
	v_mov_b32_e32 v36, v2
	v_mov_b32_e32 v37, v2
	v_mov_b32_e32 v38, v2
	v_mov_b32_e32 v39, v2
	v_mov_b32_e32 v40, v2
	v_mov_b32_e32 v41, v2
	v_mov_b32_e32 v50, v2
	v_mov_b32_e32 v51, v2
	v_mov_b32_e32 v52, v2
	v_mov_b32_e32 v53, v2
	v_mov_b32_e32 v54, v2
	v_mov_b32_e32 v55, v2
	v_mov_b32_e32 v56, v2
	v_mov_b32_e32 v57, v2
	v_mov_b32_e32 v10, v2
	v_mov_b32_e32 v11, v2
	v_mov_b32_e32 v12, v2
	v_mov_b32_e32 v13, v2
	v_mov_b32_e32 v14, v2
	v_mov_b32_e32 v15, v2
	v_mov_b32_e32 v16, v2
	v_mov_b32_e32 v17, v2
	v_mov_b32_e32 v26, v2
	v_mov_b32_e32 v27, v2
	v_mov_b32_e32 v28, v2
	v_mov_b32_e32 v29, v2
	v_mov_b32_e32 v30, v2
	v_mov_b32_e32 v31, v2
	v_mov_b32_e32 v32, v2
	v_mov_b32_e32 v33, v2
	v_mov_b32_e32 v42, v2
	v_mov_b32_e32 v43, v2
	v_mov_b32_e32 v44, v2
	v_mov_b32_e32 v45, v2
	v_mov_b32_e32 v46, v2
	v_mov_b32_e32 v47, v2
	v_mov_b32_e32 v48, v2
	v_mov_b32_e32 v49, v2
	v_mov_b32_e32 v58, v2
	v_mov_b32_e32 v59, v2
	v_mov_b32_e32 v60, v2
	v_mov_b32_e32 v61, v2
	v_mov_b32_e32 v62, v2
	v_mov_b32_e32 v63, v2
	v_mov_b32_e32 v64, v2
	v_mov_b32_e32 v65, v2
	v_mov_b32_e32 v66, v2
	v_mov_b32_e32 v67, v2
	v_mov_b32_e32 v68, v2
	v_mov_b32_e32 v69, v2
	v_mov_b32_e32 v70, v2
	v_mov_b32_e32 v71, v2
	v_mov_b32_e32 v72, v2
	v_mov_b32_e32 v73, v2
	v_mov_b32_e32 v82, v2
	v_mov_b32_e32 v83, v2
	v_mov_b32_e32 v84, v2
	v_mov_b32_e32 v85, v2
	v_mov_b32_e32 v86, v2
	v_mov_b32_e32 v87, v2
	v_mov_b32_e32 v88, v2
	v_mov_b32_e32 v89, v2
	v_mov_b32_e32 v98, v2
	v_mov_b32_e32 v99, v2
	v_mov_b32_e32 v100, v2
	v_mov_b32_e32 v101, v2
	v_mov_b32_e32 v102, v2
	v_mov_b32_e32 v103, v2
	v_mov_b32_e32 v104, v2
	v_mov_b32_e32 v105, v2
	v_mov_b32_e32 v114, v2
	v_mov_b32_e32 v115, v2
	v_mov_b32_e32 v116, v2
	v_mov_b32_e32 v117, v2
	v_mov_b32_e32 v118, v2
	v_mov_b32_e32 v119, v2
	v_mov_b32_e32 v120, v2
	v_mov_b32_e32 v121, v2
	v_mov_b32_e32 v74, v2
	v_mov_b32_e32 v75, v2
	v_mov_b32_e32 v76, v2
	v_mov_b32_e32 v77, v2
	v_mov_b32_e32 v78, v2
	v_mov_b32_e32 v79, v2
	v_mov_b32_e32 v80, v2
	v_mov_b32_e32 v81, v2
	v_mov_b32_e32 v90, v2
	v_mov_b32_e32 v91, v2
	v_mov_b32_e32 v92, v2
	v_mov_b32_e32 v93, v2
	v_mov_b32_e32 v94, v2
	v_mov_b32_e32 v95, v2
	v_mov_b32_e32 v96, v2
	v_mov_b32_e32 v97, v2
	v_mov_b32_e32 v106, v2
	v_mov_b32_e32 v107, v2
	v_mov_b32_e32 v108, v2
	v_mov_b32_e32 v109, v2
	v_mov_b32_e32 v110, v2
	v_mov_b32_e32 v111, v2
	v_mov_b32_e32 v112, v2
	v_mov_b32_e32 v113, v2
	v_mov_b32_e32 v122, v2
	v_mov_b32_e32 v123, v2
	v_mov_b32_e32 v124, v2
	v_mov_b32_e32 v125, v2
	v_mov_b32_e32 v126, v2
	v_mov_b32_e32 v127, v2
	v_mov_b32_e32 v128, v2
	v_mov_b32_e32 v129, v2
	s_nop 0
	s_nop 0
	s_nop 0

; __device__ __forceinline__ unsigned xb_ld(unsigned* p)              { return __hip_atomic_load(p, __ATOMIC_RELAXED, __HIP_MEMORY_SCOPE_AGENT); }
; __device__ __forceinline__ unsigned xb_add(unsigned* p, unsigned v) { return __hip_atomic_fetch_add(p, v, __ATOMIC_RELAXED, __HIP_MEMORY_SCOPE_AGENT); }
; #define XB_SPIN(cond, bar) do { unsigned _sp = 0; while (cond) { __builtin_amdgcn_s_sleep(1); \
;     if ((++_sp & 255u) == 0u) { if (xb_ld(&(bar)[XB_TMO])) break; if (_sp > XB_SPIN_CAP) { atomicAdd(&(bar)[XB_TMO], 1u); break; } } } } while (0)
; #define MK_TID() (wave0 * 64 + (int)__builtin_amdgcn_mbcnt_hi(~0u, __builtin_amdgcn_mbcnt_lo(~0u, 0u)))
; __device__ __forceinline__ void xcd_barrier(const XcdBarrier& b, const bool leader) {
;     ...
;             xb_add(&bar[XB_XGEN(b.x)], 1u);
;             asm volatile("s_waitcnt vmcnt(0)" ::: "memory");
;         } else {
;             XB_SPIN(xb_ld(&bar[XB_XGEN(b.x)]) == gen, bar);
;             __builtin_amdgcn_fence(__ATOMIC_ACQUIRE, "agent");
;             asm volatile("s_waitcnt vmcnt(0)" ::: "memory");
; __global__ void __launch_bounds__(NTHREADS, 2) fwd_megakernel(Args a) {
;     ...
;     { pg8::Gemm g{ACT, W2OT, T_P, 1024, 2816}; pg8::StaticOrder S; S.init(T_P, 1024, G, bx); pg8::EpiRes E{nullptr, nullptr, 1 << 30, XN, nullptr, XN, nullptr, 0.5f};
;       pg8::gemm_phase<pg8::EpiRes, pg8::StaticOrder, true, true>(lds, g, S, E, MK_TID()); }
.LBB0_1146:
	s_or_b64 exec, exec, s[10:11]
	s_mov_b64 s[10:11], exec
	v_mbcnt_lo_u32_b32 v0, s10, 0
	v_mbcnt_hi_u32_b32 v0, s11, v0
	v_cmp_eq_u32_e32 vcc, 0, v0
	s_waitcnt vmcnt(0)
	s_and_saveexec_b64 s[12:13], vcc
	s_cbranch_execz .LBB0_1148
	s_bcnt1_i32_b64 s0, s[10:11]
	v_mov_b32_e32 v0, 0x2000
	v_mov_b32_e32 v1, s0
.LBB0_1148:
	s_or_b64 exec, exec, s[12:13]
.LBB0_1149:
	s_or_b64 exec, exec, s[4:5]
	s_load_dwordx4 s[4:7], s[90:91], 0xa8
	s_mov_b64 s[0:1], 0
	s_waitcnt lgkmcnt(0)
	s_barrier
	s_add_u32 s4, s6, s0
	s_addc_u32 s5, s7, s1
	v_readlane_b32 s2, v251, 61
	s_add_u32 s0, s4, 0x3200000
	v_mov_b32_e32 v8, v201
	v_readlane_b32 s3, v251, 62
	s_addc_u32 s1, s5, 0
	s_and_b64 vcc, exec, s[2:3]
	v_readfirstlane_b32 s10, v8
	s_cbranch_vccnz .LBB0_1177
	v_readlane_b32 s2, v251, 12
	v_readlane_b32 s3, v251, 13
	s_and_b64 vcc, exec, s[2:3]
	s_cbranch_vccz .LBB0_1152
	s_lshl_b32 s12, s58, 6
	s_cbranch_execz .LBB0_1153
	s_branch .LBB0_1154

; template <class Epi, class Sched, bool ALIGN_EPI = false, bool SP2 = false>
; __device__ __forceinline__ void gemm_phase(PG8_LAS unsigned char* lds, const Gemm g, const Sched& S, const Epi& E, const int tid_arg) {
;     ...
;         for (int a = 0; a < 2; ++a)
; #pragma unroll
;             for (int b = 0; b < 2; ++b)
; #pragma unroll
;                 for (int m = 0; m < 4; ++m)
; #pragma unroll
;                     for (int n = 0; n < 2; ++n) acc[a][b][m][n] = (f32x4){0.f, 0.f, 0.f, 0.f};
;         cur = nxt; cA = nA; cB = nB; ++ui;
.LBB0_1169:
	s_add_u32 s23, s26, 0x100
	v_mov_b32_e32 v0, 0
	s_addc_u32 s46, s27, 0
	s_mov_b32 s47, -2
	v_mov_b32_e32 v1, v0
	v_mov_b32_e32 v2, v0
	v_mov_b32_e32 v3, v0
	v_mov_b32_e32 v4, v0
	v_mov_b32_e32 v5, v0
	v_mov_b32_e32 v6, v0
	v_mov_b32_e32 v7, v0
	v_mov_b32_e32 v16, v0
	v_mov_b32_e32 v17, v0
	v_mov_b32_e32 v18, v0
	v_mov_b32_e32 v19, v0
	v_mov_b32_e32 v20, v0
	v_mov_b32_e32 v21, v0
	v_mov_b32_e32 v22, v0
	v_mov_b32_e32 v23, v0
	v_mov_b32_e32 v32, v0
	v_mov_b32_e32 v33, v0
	v_mov_b32_e32 v34, v0
	v_mov_b32_e32 v35, v0
	v_mov_b32_e32 v36, v0
	v_mov_b32_e32 v37, v0
	v_mov_b32_e32 v38, v0
	v_mov_b32_e32 v39, v0
	v_mov_b32_e32 v48, v0
	v_mov_b32_e32 v49, v0
	v_mov_b32_e32 v50, v0
	v_mov_b32_e32 v51, v0
	v_mov_b32_e32 v52, v0
	v_mov_b32_e32 v53, v0
	v_mov_b32_e32 v54, v0
	v_mov_b32_e32 v55, v0
	v_mov_b32_e32 v8, v0
	v_mov_b32_e32 v9, v0
	v_mov_b32_e32 v10, v0
	v_mov_b32_e32 v11, v0
	v_mov_b32_e32 v12, v0
	v_mov_b32_e32 v13, v0
	v_mov_b32_e32 v14, v0
	v_mov_b32_e32 v15, v0
	v_mov_b32_e32 v24, v0
	v_mov_b32_e32 v25, v0
	v_mov_b32_e32 v26, v0
	v_mov_b32_e32 v27, v0
	v_mov_b32_e32 v28, v0
	v_mov_b32_e32 v29, v0
	v_mov_b32_e32 v30, v0
	v_mov_b32_e32 v31, v0
	v_mov_b32_e32 v40, v0
	v_mov_b32_e32 v41, v0
	v_mov_b32_e32 v42, v0
	v_mov_b32_e32 v43, v0
	v_mov_b32_e32 v44, v0
	v_mov_b32_e32 v45, v0
	v_mov_b32_e32 v46, v0
	v_mov_b32_e32 v47, v0
	v_mov_b32_e32 v56, v0
	v_mov_b32_e32 v57, v0
	v_mov_b32_e32 v58, v0
	v_mov_b32_e32 v59, v0
	v_mov_b32_e32 v60, v0
	v_mov_b32_e32 v61, v0
	v_mov_b32_e32 v62, v0
	v_mov_b32_e32 v63, v0
	v_mov_b32_e32 v64, v0
	v_mov_b32_e32 v65, v0
	v_mov_b32_e32 v66, v0
	v_mov_b32_e32 v67, v0
	v_mov_b32_e32 v68, v0
	v_mov_b32_e32 v69, v0
	v_mov_b32_e32 v70, v0
	v_mov_b32_e32 v71, v0
	v_mov_b32_e32 v80, v0
	v_mov_b32_e32 v81, v0
	v_mov_b32_e32 v82, v0
	v_mov_b32_e32 v83, v0
	v_mov_b32_e32 v84, v0
	v_mov_b32_e32 v85, v0
	v_mov_b32_e32 v86, v0
	v_mov_b32_e32 v87, v0
	v_mov_b32_e32 v96, v0
	v_mov_b32_e32 v97, v0
	v_mov_b32_e32 v98, v0
	v_mov_b32_e32 v99, v0
	v_mov_b32_e32 v100, v0
	v_mov_b32_e32 v101, v0
	v_mov_b32_e32 v102, v0
	v_mov_b32_e32 v103, v0
	v_mov_b32_e32 v112, v0
	v_mov_b32_e32 v113, v0
	v_mov_b32_e32 v114, v0
	v_mov_b32_e32 v115, v0
	v_mov_b32_e32 v116, v0
	v_mov_b32_e32 v117, v0
	v_mov_b32_e32 v118, v0
	v_mov_b32_e32 v119, v0
	v_mov_b32_e32 v72, v0
	v_mov_b32_e32 v73, v0
	v_mov_b32_e32 v74, v0
	v_mov_b32_e32 v75, v0
	v_mov_b32_e32 v76, v0
	v_mov_b32_e32 v77, v0
	v_mov_b32_e32 v78, v0
	v_mov_b32_e32 v79, v0
	v_mov_b32_e32 v88, v0
	v_mov_b32_e32 v89, v0
	v_mov_b32_e32 v90, v0
	v_mov_b32_e32 v91, v0
	v_mov_b32_e32 v92, v0
	v_mov_b32_e32 v93, v0
	v_mov_b32_e32 v94, v0
	v_mov_b32_e32 v95, v0
	v_mov_b32_e32 v104, v0
	v_mov_b32_e32 v105, v0
	v_mov_b32_e32 v106, v0
	v_mov_b32_e32 v107, v0
	v_mov_b32_e32 v108, v0
	v_mov_b32_e32 v109, v0
	v_mov_b32_e32 v110, v0
	v_mov_b32_e32 v111, v0
	v_mov_b32_e32 v120, v0
	v_mov_b32_e32 v121, v0
	v_mov_b32_e32 v122, v0
	v_mov_b32_e32 v123, v0
	v_mov_b32_e32 v124, v0
	v_mov_b32_e32 v125, v0
	v_mov_b32_e32 v126, v0
	v_mov_b32_e32 v127, v0
	s_nop 0
	s_nop 0
	s_nop 0
	s_nop 0
	s_nop 0
	s_nop 0
	s_nop 0
	s_nop 0
	s_nop 0
	s_nop 0
	s_nop 0
	s_nop 0
	s_nop 0
	s_nop 0

; __device__ __forceinline__ float bflo(unsigned w) { return __uint_as_float(w << 16); }
; __device__ __forceinline__ float bfhi(unsigned w) { return __uint_as_float(w & 0xffff0000u); }
; #define AIN(i) arg_in(i)
; __device__ __forceinline__ unsigned xb_ld(unsigned* p)              { return __hip_atomic_load(p, __ATOMIC_RELAXED, __HIP_MEMORY_SCOPE_AGENT); }
; __device__ __forceinline__ unsigned xb_add(unsigned* p, unsigned v) { return __hip_atomic_fetch_add(p, v, __ATOMIC_RELAXED, __HIP_MEMORY_SCOPE_AGENT); }
; #define XB_SPIN(cond, bar) do { unsigned _sp = 0; while (cond) { __builtin_amdgcn_s_sleep(1); \
;     if ((++_sp & 255u) == 0u) { if (xb_ld(&(bar)[XB_TMO])) break; if (_sp > XB_SPIN_CAP) { atomicAdd(&(bar)[XB_TMO], 1u); break; } } } } while (0)
; #define LAUNDER_TID() int tid = MK_TID(); asm volatile("" : "+v"(tid)); const int lane = tid & 63, wave = __builtin_amdgcn_readfirstlane(tid >> 6)
; __device__ __forceinline__ void xcd_barrier(const XcdBarrier& b, const bool leader) {
;     ...
;             xb_add(&bar[XB_XGEN(b.x)], 1u);
;             asm volatile("s_waitcnt vmcnt(0)" ::: "memory");
;         } else {
;             XB_SPIN(xb_ld(&bar[XB_XGEN(b.x)]) == gen, bar);
;             __builtin_amdgcn_fence(__ATOMIC_ACQUIRE, "agent");
;             asm volatile("s_waitcnt vmcnt(0)" ::: "memory");
;         }
;     }
;     __syncthreads();
; __global__ void __launch_bounds__(NTHREADS, 2) fwd_megakernel(Args a) {
;     ...
;     {
;         LAUNDER_TID();
;         const int gw = bx * NWAVES + wave, NGW = G * NWAVES; const f32x4* gf = (const f32x4*)AIN(20) + lane;
;         f32x4 gv[4];
; #pragma unroll
;         for (int j = 0; j < 4; ++j) gv[j] = gf[64 * j];
;         for (int m4 = gw; m4 < T_ALL / 4; m4 += NGW) { f32x4* xr = (f32x4*)(H + (size_t)m4 * 4096) + lane; const u32x2* hb = (const u32x2*)(XN + (size_t)m4 * 4096) + lane; f32x4 v[4][4]; float s[4];
; #pragma unroll
;             for (int q = 0; q < 4; ++q)
; #pragma unroll
;                 for (int j = 0; j < 4; ++j) { const u32x2 w = hb[q * 256 + 64 * j]; v[q][j] = (f32x4){bflo(w.x), bfhi(w.x), bflo(w.y), bfhi(w.y)}; }
.LBB0_1229:
	s_or_b64 exec, exec, s[4:5]
	s_mov_b64 s[4:5], exec
	v_mbcnt_lo_u32_b32 v0, s4, 0
	v_mbcnt_hi_u32_b32 v0, s5, v0
	v_cmp_eq_u32_e32 vcc, 0, v0
	s_waitcnt vmcnt(0)
	s_and_saveexec_b64 s[8:9], vcc
	s_cbranch_execz .LBB0_1231
	s_bcnt1_i32_b64 s0, s[4:5]
	v_mov_b32_e32 v0, 0x2000
	v_mov_b32_e32 v1, s0
.LBB0_1231:
	s_or_b64 exec, exec, s[8:9]
.LBB0_1232:
	s_or_b64 exec, exec, s[2:3]
	s_mov_b64 s[2:3], 0
	s_waitcnt lgkmcnt(0)
	s_barrier
	s_nop 0
	v_readfirstlane_b32 s0, v201
	s_ashr_i32 s0, s0, 6
	s_add_i32 s6, s0, s55
	s_cmpk_lt_i32 s6, 0x2080
	s_cbranch_scc0 .LBB0_1235
	s_load_dwordx2 s[0:1], s[90:91], 0xa0
	v_and_b32_e32 v20, 63, v201
	v_lshlrev_b32_e32 v18, 4, v20
	s_ashr_i32 s7, s6, 31
	s_lshl_b64 s[4:5], s[2:3], 2
	s_waitcnt lgkmcnt(0)
	global_load_dwordx4 v[0:3], v18, s[0:1]
	global_load_dwordx4 v[4:7], v18, s[0:1] offset:1024
	global_load_dwordx4 v[8:11], v18, s[0:1] offset:2048
	global_load_dwordx4 v[12:15], v18, s[0:1] offset:3072
	s_lshl_b64 s[0:1], s[6:7], 14
	v_readlane_b32 s8, v251, 0
	v_readlane_b32 s9, v251, 1
	s_add_u32 s4, s8, s4
	s_addc_u32 s5, s9, s5
	s_add_u32 s0, s4, s0
	v_mov_b32_e32 v19, 0
	s_addc_u32 s1, s5, s1
	v_lshl_add_u64 v[16:17], s[0:1], 0, v[18:19]
	s_mov_b64 s[0:1], 0x3c00
	s_ashr_i32 s67, s66, 31
	v_lshl_add_u64 v[16:17], v[16:17], 0, s[0:1]
	s_lshl_b64 s[8:9], s[66:67], 14
	s_lshl_b64 s[0:1], s[6:7], 13
	s_add_u32 s0, s2, s0
	v_readlane_b32 s10, v251, 2
	s_addc_u32 s1, s3, s1
	v_readlane_b32 s11, v251, 3
	s_add_u32 s0, s10, s0
	v_lshlrev_b32_e32 v18, 3, v20
	s_addc_u32 s1, s11, s1
	v_lshl_add_u64 v[18:19], s[0:1], 0, v[18:19]
	s_mov_b64 s[0:1], 0x4781e00
	v_lshl_add_u64 v[18:19], v[18:19], 0, s[0:1]
	s_mov_b32 s0, 0x358637bd
	s_lshl_b64 s[10:11], s[66:67], 13
	s_movk_i32 s7, 0xf000
	s_mov_b32 s12, 0x3a800000
	v_mov_b64_e32 v[20:21], s[0:1]
	s_mov_b32 s13, 0x800000
	s_movk_i32 s14, 0xd000
	s_movk_i32 s15, 0xe000
